# in-proj k-loop: ds_read_b128 fragment loads hoisted above the previous MFMAs where registers allow (91 reads moved)
# speedup vs baseline: 1.0084x; 1.0084x over previous
; #define MFMA(a, b, c) __builtin_amdgcn_mfma_f32_32x32x16_bf16((a), (b), (c), 0, 0, 0)
;     ...
;   const int tid = opaque_tid(), lane = tid & 63, h = lane >> 5, r = lane & 31;
;   const int nk = K >> 6;
;   const int cch = (tid & 7) ^ ((tid >> 4) & 7);
;   const u16* ga = A + (size_t)(tid >> 3) * lda + cch * 8;
;   const u16* gb = Bt + (size_t)(tid >> 3) * ldb + cch * 8;
;   char* lds_t = smem + tid * 16;
;   auto issue_piece = [&](int kt, int pc) {
;     char* st = lds_t + (kt % NSTG) * STAGE;
;     if (pc < 4)
;       __builtin_amdgcn_global_load_lds((const unsigned*)(ga + (size_t)(64 * pc) * lda + (size_t)kt * ksa), (unsigned __attribute__((address_space(3)))*)(st + pc * 8192), 16, 0, 0);
;     else
;       __builtin_amdgcn_global_load_lds((const unsigned*)(gb + (size_t)(64 * (pc - 4)) * ldb + (size_t)kt * ksb), (unsigned __attribute__((address_space(3)))*)(st + ABYTES + (pc - 4) * 8192), 16, 0, 0);
;   };
;   const int x = (r >> 1) & 7;
;   int xo[4];
; #pragma unroll
;   for (int s = 0; s < 4; ++s) xo[s] = (((2 * s + h) ^ x) << 4);
;   asm volatile("s_waitcnt vmcnt(0)" ::: "memory");
; #pragma unroll
;   for (int d = 0; d < DIST; ++d)
; #pragma unroll
;     for (int pc = 0; pc < NLD; ++pc) issue_piece(d, pc);
;   pre();
;   for (int kt = 0; kt < nk; ++kt) {
;     if (DIST == 2 && kt + 1 < nk) {
;       if (NLD == 6) asm volatile("s_waitcnt vmcnt(6)" ::: "memory");
;       else if (NLD == 5) asm volatile("s_waitcnt vmcnt(5)" ::: "memory");
;       else asm volatile("s_waitcnt vmcnt(8)" ::: "memory");
;     } else {
;       asm volatile("s_waitcnt vmcnt(0)" ::: "memory");
;     }
;     __builtin_amdgcn_s_barrier();
;     const bool pre = (kt + DIST < nk);
;     const char* base = smem + (kt % NSTG) * STAGE;
;     const char* pa = base + (wrow_act + r) * 128;
;     const char* pw = base + ABYTES + (wrow_w + r) * 128;
;     constexpr int NM = NI * MJ;
;     constexpr int PPS = (NLD + 1) / 2;
; #pragma unroll
;     for (int s = 0; s < 4; ++s) {
;       bf16x8 af[MJ], wf[NI];
; #pragma unroll
;       for (int j = 0; j < MJ; ++j) af[j] = *(const bf16x8*)(pa + j * 32 * 128 + xo[s]);
; #pragma unroll
;       for (int i = 0; i < NI; ++i) wf[i] = *(const bf16x8*)(pw + i * 32 * 128 + xo[s]);
; #pragma unroll
;       for (int m = 0; m < NM; ++m) {
;         const int i = m / MJ, j = m % MJ;
;         acc[i][j] = MFMA(wf[i], af[j], acc[i][j]);
.LBB0_353:
	s_ashr_i32 s53, s52, 31
	s_lshl_b64 s[0:1], s[52:53], 19
	s_add_u32 s0, s22, s0
	v_mov_b32_e32 v4, v147
	s_addc_u32 s1, s23, s1
	s_ashr_i32 s51, s50, 31
	s_lshl_b64 s[2:3], s[50:51], 19
	v_lshrrev_b32_e32 v0, 4, v4
	v_xor_b32_e32 v5, v0, v4
	v_ashrrev_i32_e32 v0, 3, v4
	s_add_u32 s2, s24, s2
	v_ashrrev_i32_e32 v1, 31, v0
	s_addc_u32 s3, s25, s3
	v_lshlrev_b64 v[0:1], 7, v[0:1]
	v_lshlrev_b32_e32 v5, 4, v5
	v_lshl_add_u32 v184, v4, 4, 0
	v_lshl_add_u64 v[2:3], s[2:3], 0, v[0:1]
	v_lshl_add_u64 v[0:1], s[0:1], 0, v[0:1]
	v_and_b32_e32 v144, 0x70, v5
	v_readfirstlane_b32 s15, v184
	v_add_u32_e32 v183, 0x2000, v184
	v_lshl_add_u64 v[130:131], v[0:1], 0, v[144:145]
	s_waitcnt vmcnt(0)
	s_mov_b32 m0, s15
	s_mov_b64 s[0:1], 0x2000
	v_readfirstlane_b32 s14, v183
	v_add_u32_e32 v182, 0x4000, v184
	global_load_lds_dwordx4 v[130:131], off
	v_lshl_add_u64 v[0:1], v[130:131], 0, s[0:1]
	s_mov_b32 m0, s14
	s_mov_b64 s[2:3], 0x4000
	v_readfirstlane_b32 s13, v182
	v_add_u32_e32 v181, 0x6000, v184
	v_add_u32_e32 v162, 0x8000, v184
	global_load_lds_dwordx4 v[0:1], off
	v_lshl_add_u64 v[0:1], v[130:131], 0, s[2:3]
	s_mov_b32 m0, s13
	s_mov_b64 s[4:5], 0x6000
	v_readfirstlane_b32 s12, v181
	global_load_lds_dwordx4 v[0:1], off
	v_lshl_add_u64 v[0:1], v[130:131], 0, s[4:5]
	s_mov_b32 m0, s12
	v_readfirstlane_b32 s11, v162
	v_add_u32_e32 v165, 0xa000, v184
	v_lshl_add_u64 v[128:129], v[2:3], 0, v[144:145]
	global_load_lds_dwordx4 v[0:1], off
	s_mov_b32 m0, s11
	v_readfirstlane_b32 s10, v165
	v_add_u32_e32 v164, 0xc000, v184
	global_load_lds_dwordx4 v[128:129], off
	v_lshl_add_u64 v[0:1], v[128:129], 0, s[0:1]
	s_mov_b32 m0, s10
	v_readfirstlane_b32 s9, v164
	v_add_u32_e32 v163, 0xe000, v184
	global_load_lds_dwordx4 v[0:1], off
	v_lshl_add_u64 v[0:1], v[128:129], 0, s[2:3]
	s_mov_b32 m0, s9
	v_readfirstlane_b32 s8, v163
	global_load_lds_dwordx4 v[0:1], off
	v_lshl_add_u64 v[0:1], v[128:129], 0, s[4:5]
	s_mov_b32 m0, s8
	v_bfe_u32 v17, v4, 1, 3
	global_load_lds_dwordx4 v[0:1], off
	v_lshrrev_b32_e32 v0, 5, v4
	v_bfe_u32 v16, v4, 5, 1
	v_bitop3_b32 v0, v0, v17, 1 bitop3:0x6c
	v_lshlrev_b32_e32 v142, 4, v0
	v_bitop3_b32 v0, v16, v17, 2 bitop3:0x36
	v_lshlrev_b32_e32 v143, 4, v0
	v_and_b32_e32 v0, 31, v4
	v_lshlrev_b32_e32 v144, 7, v0
	v_add_u32_e32 v151, v149, v144
	v_add_u32_e32 v132, v151, v142
	v_or_b32_e32 v4, v0, v146
	s_waitcnt vmcnt(0)
	s_barrier
	ds_read_b128 v[0:3], v132 offset:32768
	v_lshlrev_b32_e32 v152, 7, v4
	v_add_u32_e32 v153, 0, v152
	v_add_u32_e32 v136, v153, v142
	ds_read_b128 v[4:7], v136
	v_bitop3_b32 v8, v16, v17, 4 bitop3:0x36
	v_lshlrev_b32_e32 v185, 4, v8
	ds_read_b128 v[8:11], v136 offset:4096
	ds_read_b128 v[12:15], v132 offset:36864
	s_waitcnt lgkmcnt(0)
	v_mfma_f32_32x32x16_bf16 v[96:111], v[0:3], v[4:7], 0
	v_bitop3_b32 v16, v16, v17, 6 bitop3:0x36
	v_lshlrev_b32_e32 v210, 4, v16
	ds_read_b128 v[16:19], v132 offset:40960
	ds_read_b128 v[138:141], v132 offset:45056
	v_add_u32_e32 v155, 0x10000, v184
	v_lshl_add_u64 v[134:135], v[128:129], 0, s[34:35]
	v_add_u32_e32 v154, 0x18000, v184
	v_mfma_f32_32x32x16_bf16 v[64:79], v[0:3], v[8:11], 0
	v_readfirstlane_b32 s3, v155
	v_lshl_add_u64 v[0:1], v[130:131], 0, s[34:35]
	s_mov_b32 m0, s3
	s_nop 0
	global_load_lds_dwordx4 v[0:1], off
	v_mfma_f32_32x32x16_bf16 v[112:127], v[12:15], v[4:7], 0
	v_mfma_f32_32x32x16_bf16 v[80:95], v[12:15], v[8:11], 0
	v_add_u32_e32 v158, 0x12000, v184
	s_mov_b64 s[6:7], 0xa000
	v_readfirstlane_b32 s2, v158
	v_lshl_add_u64 v[0:1], v[130:131], 0, s[6:7]
	s_mov_b32 m0, s2
	s_nop 0
	global_load_lds_dwordx4 v[0:1], off
	s_waitcnt lgkmcnt(0)
	v_mfma_f32_32x32x16_bf16 v[48:63], v[16:19], v[4:7], 0
	v_mfma_f32_32x32x16_bf16 v[16:31], v[16:19], v[8:11], 0
	v_add_u32_e32 v157, 0x14000, v184
	v_lshl_add_u64 v[0:1], v[130:131], 0, s[60:61]
	v_readfirstlane_b32 s1, v157
	s_mov_b32 m0, s1
	s_nop 0
	global_load_lds_dwordx4 v[0:1], off
	v_mfma_f32_32x32x16_bf16 v[32:47], v[138:141], v[4:7], 0
	v_mfma_f32_32x32x16_bf16 v[0:15], v[138:141], v[8:11], 0
	v_add_u32_e32 v156, 0x16000, v184
	v_lshl_add_u64 v[138:139], v[130:131], 0, s[36:37]
	v_readfirstlane_b32 s0, v156
	s_mov_b32 m0, s0
	s_nop 0
	global_load_lds_dwordx4 v[138:139], off
	v_add_u32_e32 v133, v151, v143
	ds_read_b128 v[138:141], v133 offset:32768
	v_add_u32_e32 v137, v153, v143
	ds_read_b128 v[186:189], v137
	ds_read_b128 v[190:193], v137 offset:4096
	ds_read_b128 v[194:197], v133 offset:36864
	ds_read_b128 v[198:201], v133 offset:40960
	ds_read_b128 v[202:205], v133 offset:45056
	s_waitcnt lgkmcnt(0)
	v_mfma_f32_32x32x16_bf16 v[96:111], v[138:141], v[186:189], v[96:111]
	v_mfma_f32_32x32x16_bf16 v[64:79], v[138:141], v[190:193], v[64:79]
	v_readfirstlane_b32 s4, v154
	s_mov_b32 m0, s4
	s_nop 0
	global_load_lds_dwordx4 v[134:135], off
	v_mfma_f32_32x32x16_bf16 v[112:127], v[194:197], v[186:189], v[112:127]
	v_mfma_f32_32x32x16_bf16 v[80:95], v[194:197], v[190:193], v[80:95]
	v_add_u32_e32 v159, 0x1a000, v184
	v_lshl_add_u64 v[134:135], v[128:129], 0, s[6:7]
	v_readfirstlane_b32 s5, v159
	s_mov_b32 m0, s5
	s_nop 0
	global_load_lds_dwordx4 v[134:135], off
	v_mfma_f32_32x32x16_bf16 v[48:63], v[198:201], v[186:189], v[48:63]
	v_mfma_f32_32x32x16_bf16 v[16:31], v[198:201], v[190:193], v[16:31]
	v_add_u32_e32 v160, 0x1c000, v184
	v_lshl_add_u64 v[134:135], v[128:129], 0, s[60:61]
	v_readfirstlane_b32 s6, v160
	s_mov_b32 m0, s6
	s_nop 0
	global_load_lds_dwordx4 v[134:135], off
	v_mfma_f32_32x32x16_bf16 v[32:47], v[202:205], v[186:189], v[32:47]
	v_mfma_f32_32x32x16_bf16 v[0:15], v[202:205], v[190:193], v[0:15]
	v_add_u32_e32 v161, 0x1e000, v184
	v_lshl_add_u64 v[134:135], v[128:129], 0, s[36:37]
	v_readfirstlane_b32 s7, v161
	s_mov_b32 m0, s7
	s_nop 0
	global_load_lds_dwordx4 v[134:135], off
	v_add_u32_e32 v135, v151, v185
	ds_read_b128 v[186:189], v135 offset:32768
	v_add_u32_e32 v140, v153, v185
	ds_read_b128 v[190:193], v140
	ds_read_b128 v[194:197], v140 offset:4096
	ds_read_b128 v[198:201], v135 offset:36864
	v_add_u32_e32 v134, v151, v210
	v_add_u32_e32 v139, v153, v210
	s_waitcnt lgkmcnt(0)
; #define MFMA(a, b, c) __builtin_amdgcn_mfma_f32_32x32x16_bf16((a), (b), (c), 0, 0, 0)
;     ...
;     const bool pre = (kt + DIST < nk);
;     const char* base = smem + (kt % NSTG) * STAGE;
;     const char* pa = base + (wrow_act + r) * 128;
;     const char* pw = base + ABYTES + (wrow_w + r) * 128;
;     constexpr int NM = NI * MJ;
;     constexpr int PPS = (NLD + 1) / 2;
; #pragma unroll
;     for (int s = 0; s < 4; ++s) {
;       bf16x8 af[MJ], wf[NI];
; #pragma unroll
;       for (int j = 0; j < MJ; ++j) af[j] = *(const bf16x8*)(pa + j * 32 * 128 + xo[s]);
; #pragma unroll
;       for (int i = 0; i < NI; ++i) wf[i] = *(const bf16x8*)(pw + i * 32 * 128 + xo[s]);
; #pragma unroll
;       for (int m = 0; m < NM; ++m) {
;         const int i = m / MJ, j = m % MJ;
;         acc[i][j] = MFMA(wf[i], af[j], acc[i][j]);
;         if (s < 2 && NM >= PPS) {
;           constexpr int EVERY = (NM / PPS) > 0 ? (NM / PPS) : 1;
;           if ((m + 1) % EVERY == 0) {
;             const int pc = s * PPS + (m + 1) / EVERY - 1;
;             if ((m + 1) / EVERY <= PPS && pc < NLD) {
;               __builtin_amdgcn_sched_barrier(0);
;               if (pre) issue_piece(kt + DIST, pc);
;               __builtin_amdgcn_sched_barrier(0);
;             }
;           }
;         }
;         if (s < 2 && NM < PPS) {
;           const int slot = s * NM + m;
;           __builtin_amdgcn_sched_barrier(0);
; #pragma unroll
;           for (int pc = 0; pc < NLD; ++pc)
;             if ((pc * 2 * NM) / NLD == slot && pre) issue_piece(kt + DIST, pc);
;           __builtin_amdgcn_sched_barrier(0);
;         }
;       }
;     }
	v_mfma_f32_32x32x16_bf16 v[112:127], v[198:201], v[190:193], v[112:127]
	v_add_u32_e32 v141, v150, v144
	v_add_u32_e32 v138, v141, v142
	s_add_i32 s16, 0, 0x10000
	v_add_u32_e32 v211, s16, v152
	v_add_u32_e32 v142, v211, v142
	v_lshl_add_u64 v[152:153], v[128:129], 0, s[56:57]
	v_mfma_f32_32x32x16_bf16 v[96:111], v[186:189], v[190:193], v[96:111]
	v_mfma_f32_32x32x16_bf16 v[64:79], v[186:189], v[194:197], v[64:79]
	ds_read_b128 v[186:189], v135 offset:40960
	v_mfma_f32_32x32x16_bf16 v[80:95], v[198:201], v[194:197], v[80:95]
	ds_read_b128 v[198:201], v135 offset:45056
	s_waitcnt lgkmcnt(0)
	v_mfma_f32_32x32x16_bf16 v[48:63], v[186:189], v[190:193], v[48:63]
	v_mfma_f32_32x32x16_bf16 v[16:31], v[186:189], v[194:197], v[16:31]
	ds_read_b128 v[186:189], v134 offset:32768
	v_mfma_f32_32x32x16_bf16 v[32:47], v[198:201], v[190:193], v[32:47]
	ds_read_b128 v[190:193], v139
	v_mfma_f32_32x32x16_bf16 v[0:15], v[198:201], v[194:197], v[0:15]
	ds_read_b128 v[194:197], v139 offset:4096
	ds_read_b128 v[198:201], v134 offset:36864
	s_waitcnt lgkmcnt(0)
	v_mfma_f32_32x32x16_bf16 v[96:111], v[186:189], v[190:193], v[96:111]
	v_mfma_f32_32x32x16_bf16 v[64:79], v[186:189], v[194:197], v[64:79]
	ds_read_b128 v[186:189], v134 offset:40960
	v_mfma_f32_32x32x16_bf16 v[112:127], v[198:201], v[190:193], v[112:127]
	v_mfma_f32_32x32x16_bf16 v[80:95], v[198:201], v[194:197], v[80:95]
	ds_read_b128 v[198:201], v134 offset:45056
	s_waitcnt vmcnt(0)
	s_barrier
	s_waitcnt lgkmcnt(0)
	v_mfma_f32_32x32x16_bf16 v[48:63], v[186:189], v[190:193], v[48:63]
	v_mfma_f32_32x32x16_bf16 v[16:31], v[186:189], v[194:197], v[16:31]
	ds_read_b128 v[186:189], v138
	v_mfma_f32_32x32x16_bf16 v[32:47], v[198:201], v[190:193], v[32:47]
	ds_read_b128 v[190:193], v142
	v_mfma_f32_32x32x16_bf16 v[0:15], v[198:201], v[194:197], v[0:15]
	ds_read_b128 v[194:197], v142 offset:4096
	ds_read_b128 v[198:201], v138 offset:4096
	ds_read_b128 v[202:205], v138 offset:8192
	ds_read_b128 v[206:209], v138 offset:12288
	s_waitcnt lgkmcnt(0)
	v_mfma_f32_32x32x16_bf16 v[96:111], v[186:189], v[190:193], v[96:111]
	v_mfma_f32_32x32x16_bf16 v[64:79], v[186:189], v[194:197], v[64:79]
	v_lshl_add_u64 v[186:187], v[130:131], 0, s[56:57]
	s_mov_b32 m0, s15
	s_nop 0
	global_load_lds_dwordx4 v[186:187], off
	v_mfma_f32_32x32x16_bf16 v[112:127], v[198:201], v[190:193], v[112:127]
	v_mfma_f32_32x32x16_bf16 v[80:95], v[198:201], v[194:197], v[80:95]
	s_mov_b64 s[16:17], 0x12000
	v_lshl_add_u64 v[186:187], v[130:131], 0, s[16:17]
	s_mov_b32 m0, s14
	s_nop 0
	global_load_lds_dwordx4 v[186:187], off
	v_mfma_f32_32x32x16_bf16 v[48:63], v[202:205], v[190:193], v[48:63]
	v_mfma_f32_32x32x16_bf16 v[16:31], v[202:205], v[194:197], v[16:31]
	s_mov_b64 s[18:19], 0x14000
	v_lshl_add_u64 v[186:187], v[130:131], 0, s[18:19]
	s_mov_b32 m0, s13
	s_nop 0
	global_load_lds_dwordx4 v[186:187], off
	v_mfma_f32_32x32x16_bf16 v[32:47], v[206:209], v[190:193], v[32:47]
	v_mfma_f32_32x32x16_bf16 v[0:15], v[206:209], v[194:197], v[0:15]
	s_mov_b64 s[20:21], 0x16000
	v_lshl_add_u64 v[186:187], v[130:131], 0, s[20:21]
	s_mov_b32 m0, s12
	s_nop 0
	global_load_lds_dwordx4 v[186:187], off
	v_add_u32_e32 v144, v141, v143
	ds_read_b128 v[186:189], v144
	v_add_u32_e32 v151, v211, v143
	ds_read_b128 v[190:193], v151
	ds_read_b128 v[194:197], v151 offset:4096
	ds_read_b128 v[198:201], v144 offset:4096
	ds_read_b128 v[202:205], v144 offset:8192
	ds_read_b128 v[206:209], v144 offset:12288
	s_waitcnt lgkmcnt(0)
	v_mfma_f32_32x32x16_bf16 v[96:111], v[186:189], v[190:193], v[96:111]
	v_mfma_f32_32x32x16_bf16 v[64:79], v[186:189], v[194:197], v[64:79]
	s_mov_b32 m0, s11
	s_nop 0
	global_load_lds_dwordx4 v[152:153], off
	v_mfma_f32_32x32x16_bf16 v[112:127], v[198:201], v[190:193], v[112:127]
	v_mfma_f32_32x32x16_bf16 v[80:95], v[198:201], v[194:197], v[80:95]
	v_lshl_add_u64 v[152:153], v[128:129], 0, s[16:17]
	s_mov_b32 m0, s10
	s_nop 0
	global_load_lds_dwordx4 v[152:153], off
	v_mfma_f32_32x32x16_bf16 v[48:63], v[202:205], v[190:193], v[48:63]
	v_mfma_f32_32x32x16_bf16 v[16:31], v[202:205], v[194:197], v[16:31]
	v_lshl_add_u64 v[152:153], v[128:129], 0, s[18:19]
	s_mov_b32 m0, s9
	s_nop 0
	global_load_lds_dwordx4 v[152:153], off
	v_mfma_f32_32x32x16_bf16 v[32:47], v[206:209], v[190:193], v[32:47]
	v_mfma_f32_32x32x16_bf16 v[0:15], v[206:209], v[194:197], v[0:15]
	v_lshl_add_u64 v[152:153], v[128:129], 0, s[20:21]
	s_mov_b32 m0, s8
	s_nop 0
	global_load_lds_dwordx4 v[152:153], off
	v_add_u32_e32 v143, v141, v185
	ds_read_b128 v[186:189], v143
	v_add_u32_e32 v153, v211, v185
	ds_read_b128 v[190:193], v153
	ds_read_b128 v[194:197], v153 offset:4096
	ds_read_b128 v[198:201], v143 offset:4096
	v_add_u32_e32 v141, v141, v210
	v_add_u32_e32 v152, v211, v210
	s_waitcnt lgkmcnt(0)
	v_mfma_f32_32x32x16_bf16 v[112:127], v[198:201], v[190:193], v[112:127]
	v_lshl_add_u64 v[210:211], v[128:129], 0, s[58:59]
	v_mfma_f32_32x32x16_bf16 v[96:111], v[186:189], v[190:193], v[96:111]
	v_mfma_f32_32x32x16_bf16 v[64:79], v[186:189], v[194:197], v[64:79]
	ds_read_b128 v[186:189], v143 offset:8192
	v_mfma_f32_32x32x16_bf16 v[80:95], v[198:201], v[194:197], v[80:95]
	ds_read_b128 v[198:201], v143 offset:12288
	s_waitcnt lgkmcnt(0)
	v_mfma_f32_32x32x16_bf16 v[48:63], v[186:189], v[190:193], v[48:63]
	v_mfma_f32_32x32x16_bf16 v[16:31], v[186:189], v[194:197], v[16:31]
	ds_read_b128 v[186:189], v141
	v_mfma_f32_32x32x16_bf16 v[32:47], v[198:201], v[190:193], v[32:47]
	ds_read_b128 v[190:193], v152
	v_mfma_f32_32x32x16_bf16 v[0:15], v[198:201], v[194:197], v[0:15]
	ds_read_b128 v[194:197], v152 offset:4096
	ds_read_b128 v[198:201], v141 offset:4096
	s_waitcnt lgkmcnt(0)
	v_mfma_f32_32x32x16_bf16 v[96:111], v[186:189], v[190:193], v[96:111]
	v_mfma_f32_32x32x16_bf16 v[64:79], v[186:189], v[194:197], v[64:79]
	ds_read_b128 v[186:189], v141 offset:8192
	v_mfma_f32_32x32x16_bf16 v[112:127], v[198:201], v[190:193], v[112:127]
	v_mfma_f32_32x32x16_bf16 v[80:95], v[198:201], v[194:197], v[80:95]
	ds_read_b128 v[198:201], v141 offset:12288
	s_waitcnt vmcnt(0)
	s_barrier
; #define MFMA(a, b, c) __builtin_amdgcn_mfma_f32_32x32x16_bf16((a), (b), (c), 0, 0, 0)
;     ...
;     const bool pre = (kt + DIST < nk);
;     const char* base = smem + (kt % NSTG) * STAGE;
;     const char* pa = base + (wrow_act + r) * 128;
;     const char* pw = base + ABYTES + (wrow_w + r) * 128;
;     constexpr int NM = NI * MJ;
;     constexpr int PPS = (NLD + 1) / 2;
; #pragma unroll
;     for (int s = 0; s < 4; ++s) {
;       bf16x8 af[MJ], wf[NI];
; #pragma unroll
;       for (int j = 0; j < MJ; ++j) af[j] = *(const bf16x8*)(pa + j * 32 * 128 + xo[s]);
; #pragma unroll
;       for (int i = 0; i < NI; ++i) wf[i] = *(const bf16x8*)(pw + i * 32 * 128 + xo[s]);
; #pragma unroll
;       for (int m = 0; m < NM; ++m) {
;         const int i = m / MJ, j = m % MJ;
;         acc[i][j] = MFMA(wf[i], af[j], acc[i][j]);
;         if (s < 2 && NM >= PPS) {
;           constexpr int EVERY = (NM / PPS) > 0 ? (NM / PPS) : 1;
;           if ((m + 1) % EVERY == 0) {
;             const int pc = s * PPS + (m + 1) / EVERY - 1;
;             if ((m + 1) / EVERY <= PPS && pc < NLD) {
;               __builtin_amdgcn_sched_barrier(0);
;               if (pre) issue_piece(kt + DIST, pc);
;               __builtin_amdgcn_sched_barrier(0);
;             }
;           }
;         }
;         if (s < 2 && NM < PPS) {
;           const int slot = s * NM + m;
;           __builtin_amdgcn_sched_barrier(0);
; #pragma unroll
;           for (int pc = 0; pc < NLD; ++pc)
;             if ((pc * 2 * NM) / NLD == slot && pre) issue_piece(kt + DIST, pc);
;           __builtin_amdgcn_sched_barrier(0);
;         }
;       }
;     }
	s_waitcnt lgkmcnt(0)
	v_mfma_f32_32x32x16_bf16 v[48:63], v[186:189], v[190:193], v[48:63]
	v_mfma_f32_32x32x16_bf16 v[16:31], v[186:189], v[194:197], v[16:31]
	ds_read_b128 v[186:189], v132 offset:32768
	v_mfma_f32_32x32x16_bf16 v[32:47], v[198:201], v[190:193], v[32:47]
	ds_read_b128 v[190:193], v136
	v_mfma_f32_32x32x16_bf16 v[0:15], v[198:201], v[194:197], v[0:15]
	ds_read_b128 v[194:197], v136 offset:4096
	ds_read_b128 v[198:201], v132 offset:36864
	ds_read_b128 v[202:205], v132 offset:40960
	ds_read_b128 v[206:209], v132 offset:45056
	s_waitcnt lgkmcnt(0)
	v_mfma_f32_32x32x16_bf16 v[96:111], v[186:189], v[190:193], v[96:111]
	v_mfma_f32_32x32x16_bf16 v[64:79], v[186:189], v[194:197], v[64:79]
	v_lshl_add_u64 v[186:187], v[130:131], 0, s[58:59]
	s_mov_b32 m0, s3
	s_nop 0
	global_load_lds_dwordx4 v[186:187], off
	v_mfma_f32_32x32x16_bf16 v[112:127], v[198:201], v[190:193], v[112:127]
	v_mfma_f32_32x32x16_bf16 v[80:95], v[198:201], v[194:197], v[80:95]
	s_mov_b64 s[16:17], 0x1a000
	v_lshl_add_u64 v[186:187], v[130:131], 0, s[16:17]
	s_mov_b32 m0, s2
	s_nop 0
	global_load_lds_dwordx4 v[186:187], off
	v_mfma_f32_32x32x16_bf16 v[48:63], v[202:205], v[190:193], v[48:63]
	v_mfma_f32_32x32x16_bf16 v[16:31], v[202:205], v[194:197], v[16:31]
	s_mov_b64 s[18:19], 0x1c000
	v_lshl_add_u64 v[186:187], v[130:131], 0, s[18:19]
	s_mov_b32 m0, s1
	s_nop 0
	global_load_lds_dwordx4 v[186:187], off
	v_mfma_f32_32x32x16_bf16 v[32:47], v[206:209], v[190:193], v[32:47]
	v_mfma_f32_32x32x16_bf16 v[0:15], v[206:209], v[194:197], v[0:15]
	s_mov_b64 s[20:21], 0x1e000
	v_lshl_add_u64 v[186:187], v[130:131], 0, s[20:21]
	s_mov_b32 m0, s0
	s_nop 0
	global_load_lds_dwordx4 v[186:187], off
	ds_read_b128 v[186:189], v133 offset:32768
	ds_read_b128 v[190:193], v137
	ds_read_b128 v[194:197], v137 offset:4096
	ds_read_b128 v[198:201], v133 offset:36864
	ds_read_b128 v[202:205], v133 offset:40960
	ds_read_b128 v[206:209], v133 offset:45056
	s_waitcnt lgkmcnt(0)
	v_mfma_f32_32x32x16_bf16 v[96:111], v[186:189], v[190:193], v[96:111]
	v_mfma_f32_32x32x16_bf16 v[64:79], v[186:189], v[194:197], v[64:79]
	s_mov_b32 m0, s4
	s_nop 0
	global_load_lds_dwordx4 v[210:211], off
	v_mfma_f32_32x32x16_bf16 v[112:127], v[198:201], v[190:193], v[112:127]
	v_mfma_f32_32x32x16_bf16 v[80:95], v[198:201], v[194:197], v[80:95]
	v_lshl_add_u64 v[186:187], v[128:129], 0, s[16:17]
	s_mov_b32 m0, s5
	s_nop 0
	global_load_lds_dwordx4 v[186:187], off
	v_mfma_f32_32x32x16_bf16 v[48:63], v[202:205], v[190:193], v[48:63]
	v_mfma_f32_32x32x16_bf16 v[16:31], v[202:205], v[194:197], v[16:31]
	v_lshl_add_u64 v[186:187], v[128:129], 0, s[18:19]
	s_mov_b32 m0, s6
	s_nop 0
	global_load_lds_dwordx4 v[186:187], off
	v_mfma_f32_32x32x16_bf16 v[32:47], v[206:209], v[190:193], v[32:47]
	v_mfma_f32_32x32x16_bf16 v[0:15], v[206:209], v[194:197], v[0:15]
	v_lshl_add_u64 v[186:187], v[128:129], 0, s[20:21]
	s_mov_b32 m0, s7
	s_nop 0
	global_load_lds_dwordx4 v[186:187], off
	ds_read_b128 v[186:189], v135 offset:32768
	ds_read_b128 v[190:193], v140
	ds_read_b128 v[194:197], v140 offset:4096
	ds_read_b128 v[198:201], v135 offset:36864
	s_mov_b64 s[16:17], 0x20000
	v_lshl_add_u64 v[210:211], v[128:129], 0, s[16:17]
	s_waitcnt lgkmcnt(0)
	v_mfma_f32_32x32x16_bf16 v[96:111], v[186:189], v[190:193], v[96:111]
	v_mfma_f32_32x32x16_bf16 v[64:79], v[186:189], v[194:197], v[64:79]
	ds_read_b128 v[186:189], v135 offset:40960
	v_mfma_f32_32x32x16_bf16 v[112:127], v[198:201], v[190:193], v[112:127]
	v_mfma_f32_32x32x16_bf16 v[80:95], v[198:201], v[194:197], v[80:95]
	ds_read_b128 v[198:201], v135 offset:45056
	s_waitcnt lgkmcnt(0)
	v_mfma_f32_32x32x16_bf16 v[48:63], v[186:189], v[190:193], v[48:63]
	v_mfma_f32_32x32x16_bf16 v[16:31], v[186:189], v[194:197], v[16:31]
	ds_read_b128 v[186:189], v134 offset:32768
	v_mfma_f32_32x32x16_bf16 v[32:47], v[198:201], v[190:193], v[32:47]
	ds_read_b128 v[190:193], v139
	v_mfma_f32_32x32x16_bf16 v[0:15], v[198:201], v[194:197], v[0:15]
	ds_read_b128 v[194:197], v139 offset:4096
	ds_read_b128 v[198:201], v134 offset:36864
	s_waitcnt lgkmcnt(0)
	v_mfma_f32_32x32x16_bf16 v[96:111], v[186:189], v[190:193], v[96:111]
	v_mfma_f32_32x32x16_bf16 v[64:79], v[186:189], v[194:197], v[64:79]
	ds_read_b128 v[186:189], v134 offset:40960
	v_mfma_f32_32x32x16_bf16 v[112:127], v[198:201], v[190:193], v[112:127]
	v_mfma_f32_32x32x16_bf16 v[80:95], v[198:201], v[194:197], v[80:95]
	ds_read_b128 v[198:201], v134 offset:45056
	s_waitcnt vmcnt(0)
	s_barrier
; #define MFMA(a, b, c) __builtin_amdgcn_mfma_f32_32x32x16_bf16((a), (b), (c), 0, 0, 0)
;     ...
;     const bool pre = (kt + DIST < nk);
;     const char* base = smem + (kt % NSTG) * STAGE;
;     const char* pa = base + (wrow_act + r) * 128;
;     const char* pw = base + ABYTES + (wrow_w + r) * 128;
;     constexpr int NM = NI * MJ;
;     constexpr int PPS = (NLD + 1) / 2;
; #pragma unroll
;     for (int s = 0; s < 4; ++s) {
;       bf16x8 af[MJ], wf[NI];
; #pragma unroll
;       for (int j = 0; j < MJ; ++j) af[j] = *(const bf16x8*)(pa + j * 32 * 128 + xo[s]);
; #pragma unroll
;       for (int i = 0; i < NI; ++i) wf[i] = *(const bf16x8*)(pw + i * 32 * 128 + xo[s]);
; #pragma unroll
;       for (int m = 0; m < NM; ++m) {
;         const int i = m / MJ, j = m % MJ;
;         acc[i][j] = MFMA(wf[i], af[j], acc[i][j]);
;         if (s < 2 && NM >= PPS) {
;           constexpr int EVERY = (NM / PPS) > 0 ? (NM / PPS) : 1;
;           if ((m + 1) % EVERY == 0) {
;             const int pc = s * PPS + (m + 1) / EVERY - 1;
;             if ((m + 1) / EVERY <= PPS && pc < NLD) {
;               __builtin_amdgcn_sched_barrier(0);
;               if (pre) issue_piece(kt + DIST, pc);
;               __builtin_amdgcn_sched_barrier(0);
;             }
;           }
;         }
;         if (s < 2 && NM < PPS) {
;           const int slot = s * NM + m;
;           __builtin_amdgcn_sched_barrier(0);
; #pragma unroll
;           for (int pc = 0; pc < NLD; ++pc)
;             if ((pc * 2 * NM) / NLD == slot && pre) issue_piece(kt + DIST, pc);
;           __builtin_amdgcn_sched_barrier(0);
;         }
;       }
;     }
	s_waitcnt lgkmcnt(0)
	v_mfma_f32_32x32x16_bf16 v[48:63], v[186:189], v[190:193], v[48:63]
	v_mfma_f32_32x32x16_bf16 v[16:31], v[186:189], v[194:197], v[16:31]
	ds_read_b128 v[186:189], v138
	v_mfma_f32_32x32x16_bf16 v[32:47], v[198:201], v[190:193], v[32:47]
	ds_read_b128 v[190:193], v142
	v_mfma_f32_32x32x16_bf16 v[0:15], v[198:201], v[194:197], v[0:15]
	ds_read_b128 v[194:197], v142 offset:4096
	ds_read_b128 v[198:201], v138 offset:4096
	ds_read_b128 v[202:205], v138 offset:8192
	ds_read_b128 v[206:209], v138 offset:12288
	s_waitcnt lgkmcnt(0)
	v_mfma_f32_32x32x16_bf16 v[96:111], v[186:189], v[190:193], v[96:111]
	v_mfma_f32_32x32x16_bf16 v[64:79], v[186:189], v[194:197], v[64:79]
	v_lshl_add_u64 v[186:187], v[130:131], 0, s[16:17]
	s_mov_b32 m0, s15
	s_nop 0
	global_load_lds_dwordx4 v[186:187], off
	v_mfma_f32_32x32x16_bf16 v[112:127], v[198:201], v[190:193], v[112:127]
	v_mfma_f32_32x32x16_bf16 v[80:95], v[198:201], v[194:197], v[80:95]
	s_mov_b64 s[16:17], 0x22000
	v_lshl_add_u64 v[186:187], v[130:131], 0, s[16:17]
	s_mov_b32 m0, s14
	s_nop 0
	global_load_lds_dwordx4 v[186:187], off
	v_mfma_f32_32x32x16_bf16 v[48:63], v[202:205], v[190:193], v[48:63]
	v_mfma_f32_32x32x16_bf16 v[16:31], v[202:205], v[194:197], v[16:31]
	v_lshl_add_u64 v[186:187], v[130:131], 0, s[62:63]
	s_mov_b32 m0, s13
	s_nop 0
	global_load_lds_dwordx4 v[186:187], off
	v_mfma_f32_32x32x16_bf16 v[32:47], v[206:209], v[190:193], v[32:47]
	v_mfma_f32_32x32x16_bf16 v[0:15], v[206:209], v[194:197], v[0:15]
	s_mov_b64 s[14:15], 0x26000
	v_lshl_add_u64 v[186:187], v[130:131], 0, s[14:15]
	s_mov_b32 m0, s12
	s_nop 0
	global_load_lds_dwordx4 v[186:187], off
	ds_read_b128 v[186:189], v144
	ds_read_b128 v[190:193], v151
	ds_read_b128 v[194:197], v151 offset:4096
	ds_read_b128 v[198:201], v144 offset:4096
	ds_read_b128 v[202:205], v144 offset:8192
	ds_read_b128 v[206:209], v144 offset:12288
	s_waitcnt lgkmcnt(0)
	v_mfma_f32_32x32x16_bf16 v[96:111], v[186:189], v[190:193], v[96:111]
	v_mfma_f32_32x32x16_bf16 v[64:79], v[186:189], v[194:197], v[64:79]
	s_mov_b32 m0, s11
	s_nop 0
	global_load_lds_dwordx4 v[210:211], off
	v_mfma_f32_32x32x16_bf16 v[112:127], v[198:201], v[190:193], v[112:127]
	v_mfma_f32_32x32x16_bf16 v[80:95], v[198:201], v[194:197], v[80:95]
	v_lshl_add_u64 v[186:187], v[128:129], 0, s[16:17]
	s_mov_b32 m0, s10
	s_nop 0
	global_load_lds_dwordx4 v[186:187], off
	v_mfma_f32_32x32x16_bf16 v[48:63], v[202:205], v[190:193], v[48:63]
	v_mfma_f32_32x32x16_bf16 v[16:31], v[202:205], v[194:197], v[16:31]
	v_lshl_add_u64 v[186:187], v[128:129], 0, s[62:63]
	s_mov_b32 m0, s9
	s_nop 0
	global_load_lds_dwordx4 v[186:187], off
	v_mfma_f32_32x32x16_bf16 v[32:47], v[206:209], v[190:193], v[32:47]
	v_mfma_f32_32x32x16_bf16 v[0:15], v[206:209], v[194:197], v[0:15]
	v_lshl_add_u64 v[186:187], v[128:129], 0, s[14:15]
	s_mov_b32 m0, s8
	s_nop 0
	global_load_lds_dwordx4 v[186:187], off
	ds_read_b128 v[186:189], v143
	ds_read_b128 v[190:193], v153
	ds_read_b128 v[194:197], v153 offset:4096
	ds_read_b128 v[198:201], v143 offset:4096
	s_mov_b64 s[8:9], 0x28000
	v_lshl_add_u64 v[210:211], v[128:129], 0, s[8:9]
	s_waitcnt lgkmcnt(0)
	v_mfma_f32_32x32x16_bf16 v[96:111], v[186:189], v[190:193], v[96:111]
	v_mfma_f32_32x32x16_bf16 v[64:79], v[186:189], v[194:197], v[64:79]
	ds_read_b128 v[186:189], v143 offset:8192
	v_mfma_f32_32x32x16_bf16 v[112:127], v[198:201], v[190:193], v[112:127]
	v_mfma_f32_32x32x16_bf16 v[80:95], v[198:201], v[194:197], v[80:95]
	ds_read_b128 v[198:201], v143 offset:12288
	s_waitcnt lgkmcnt(0)
	v_mfma_f32_32x32x16_bf16 v[48:63], v[186:189], v[190:193], v[48:63]
	v_mfma_f32_32x32x16_bf16 v[16:31], v[186:189], v[194:197], v[16:31]
	ds_read_b128 v[186:189], v141
	v_mfma_f32_32x32x16_bf16 v[32:47], v[198:201], v[190:193], v[32:47]
	ds_read_b128 v[190:193], v152
	v_mfma_f32_32x32x16_bf16 v[0:15], v[198:201], v[194:197], v[0:15]
	ds_read_b128 v[194:197], v152 offset:4096
	ds_read_b128 v[198:201], v141 offset:4096
	s_waitcnt lgkmcnt(0)
	v_mfma_f32_32x32x16_bf16 v[96:111], v[186:189], v[190:193], v[96:111]
	v_mfma_f32_32x32x16_bf16 v[64:79], v[186:189], v[194:197], v[64:79]
	ds_read_b128 v[186:189], v141 offset:8192
	v_mfma_f32_32x32x16_bf16 v[112:127], v[198:201], v[190:193], v[112:127]
	v_mfma_f32_32x32x16_bf16 v[80:95], v[198:201], v[194:197], v[80:95]
	ds_read_b128 v[198:201], v141 offset:12288
	s_waitcnt vmcnt(0)
	s_barrier
; #define MFMA(a, b, c) __builtin_amdgcn_mfma_f32_32x32x16_bf16((a), (b), (c), 0, 0, 0)
;     ...
;     const bool pre = (kt + DIST < nk);
;     const char* base = smem + (kt % NSTG) * STAGE;
;     const char* pa = base + (wrow_act + r) * 128;
;     const char* pw = base + ABYTES + (wrow_w + r) * 128;
;     constexpr int NM = NI * MJ;
;     constexpr int PPS = (NLD + 1) / 2;
; #pragma unroll
;     for (int s = 0; s < 4; ++s) {
;       bf16x8 af[MJ], wf[NI];
; #pragma unroll
;       for (int j = 0; j < MJ; ++j) af[j] = *(const bf16x8*)(pa + j * 32 * 128 + xo[s]);
; #pragma unroll
;       for (int i = 0; i < NI; ++i) wf[i] = *(const bf16x8*)(pw + i * 32 * 128 + xo[s]);
; #pragma unroll
;       for (int m = 0; m < NM; ++m) {
;         const int i = m / MJ, j = m % MJ;
;         acc[i][j] = MFMA(wf[i], af[j], acc[i][j]);
;         if (s < 2 && NM >= PPS) {
;           constexpr int EVERY = (NM / PPS) > 0 ? (NM / PPS) : 1;
;           if ((m + 1) % EVERY == 0) {
;             const int pc = s * PPS + (m + 1) / EVERY - 1;
;             if ((m + 1) / EVERY <= PPS && pc < NLD) {
;               __builtin_amdgcn_sched_barrier(0);
;               if (pre) issue_piece(kt + DIST, pc);
;               __builtin_amdgcn_sched_barrier(0);
;             }
;           }
;         }
;         if (s < 2 && NM < PPS) {
;           const int slot = s * NM + m;
;           __builtin_amdgcn_sched_barrier(0);
; #pragma unroll
;           for (int pc = 0; pc < NLD; ++pc)
;             if ((pc * 2 * NM) / NLD == slot && pre) issue_piece(kt + DIST, pc);
;           __builtin_amdgcn_sched_barrier(0);
;         }
;       }
;     }
	s_waitcnt lgkmcnt(0)
	v_mfma_f32_32x32x16_bf16 v[48:63], v[186:189], v[190:193], v[48:63]
	v_mfma_f32_32x32x16_bf16 v[16:31], v[186:189], v[194:197], v[16:31]
	ds_read_b128 v[186:189], v132 offset:32768
	v_mfma_f32_32x32x16_bf16 v[32:47], v[198:201], v[190:193], v[32:47]
	ds_read_b128 v[190:193], v136
	v_mfma_f32_32x32x16_bf16 v[0:15], v[198:201], v[194:197], v[0:15]
	ds_read_b128 v[194:197], v136 offset:4096
	ds_read_b128 v[198:201], v132 offset:36864
	ds_read_b128 v[202:205], v132 offset:40960
	ds_read_b128 v[206:209], v132 offset:45056
	s_waitcnt lgkmcnt(0)
	v_mfma_f32_32x32x16_bf16 v[96:111], v[186:189], v[190:193], v[96:111]
	v_mfma_f32_32x32x16_bf16 v[64:79], v[186:189], v[194:197], v[64:79]
	v_lshl_add_u64 v[186:187], v[130:131], 0, s[8:9]
	s_mov_b32 m0, s3
	s_nop 0
	global_load_lds_dwordx4 v[186:187], off
	v_mfma_f32_32x32x16_bf16 v[112:127], v[198:201], v[190:193], v[112:127]
	v_mfma_f32_32x32x16_bf16 v[80:95], v[198:201], v[194:197], v[80:95]
	s_mov_b64 s[8:9], 0x2a000
	v_lshl_add_u64 v[186:187], v[130:131], 0, s[8:9]
	s_mov_b32 m0, s2
	s_nop 0
	global_load_lds_dwordx4 v[186:187], off
	v_mfma_f32_32x32x16_bf16 v[48:63], v[202:205], v[190:193], v[48:63]
	v_mfma_f32_32x32x16_bf16 v[16:31], v[202:205], v[194:197], v[16:31]
	s_mov_b64 s[2:3], 0x2c000
	v_lshl_add_u64 v[186:187], v[130:131], 0, s[2:3]
	s_mov_b32 m0, s1
	s_nop 0
	global_load_lds_dwordx4 v[186:187], off
	v_mfma_f32_32x32x16_bf16 v[32:47], v[206:209], v[190:193], v[32:47]
	v_mfma_f32_32x32x16_bf16 v[0:15], v[206:209], v[194:197], v[0:15]
	s_mov_b64 s[10:11], 0x2e000
	v_lshl_add_u64 v[186:187], v[130:131], 0, s[10:11]
	s_mov_b32 m0, s0
	s_nop 0
	global_load_lds_dwordx4 v[186:187], off
	ds_read_b128 v[186:189], v133 offset:32768
	ds_read_b128 v[190:193], v137
	ds_read_b128 v[194:197], v137 offset:4096
	ds_read_b128 v[198:201], v133 offset:36864
	ds_read_b128 v[202:205], v133 offset:40960
	ds_read_b128 v[206:209], v133 offset:45056
	s_waitcnt lgkmcnt(0)
	v_mfma_f32_32x32x16_bf16 v[96:111], v[186:189], v[190:193], v[96:111]
	v_mfma_f32_32x32x16_bf16 v[64:79], v[186:189], v[194:197], v[64:79]
	s_mov_b32 m0, s4
	s_nop 0
	global_load_lds_dwordx4 v[210:211], off
	v_mfma_f32_32x32x16_bf16 v[112:127], v[198:201], v[190:193], v[112:127]
	v_mfma_f32_32x32x16_bf16 v[80:95], v[198:201], v[194:197], v[80:95]
	v_lshl_add_u64 v[186:187], v[128:129], 0, s[8:9]
	s_mov_b32 m0, s5
	s_nop 0
	global_load_lds_dwordx4 v[186:187], off
	v_mfma_f32_32x32x16_bf16 v[48:63], v[202:205], v[190:193], v[48:63]
	v_mfma_f32_32x32x16_bf16 v[16:31], v[202:205], v[194:197], v[16:31]
	v_lshl_add_u64 v[186:187], v[128:129], 0, s[2:3]
	s_mov_b32 m0, s6
	s_nop 0
	global_load_lds_dwordx4 v[186:187], off
	v_mfma_f32_32x32x16_bf16 v[32:47], v[206:209], v[190:193], v[32:47]
	v_mfma_f32_32x32x16_bf16 v[0:15], v[206:209], v[194:197], v[0:15]
	v_lshl_add_u64 v[186:187], v[128:129], 0, s[10:11]
	s_mov_b32 m0, s7
	s_nop 0
	global_load_lds_dwordx4 v[186:187], off
	ds_read_b128 v[186:189], v135 offset:32768
	ds_read_b128 v[190:193], v140
	ds_read_b128 v[194:197], v140 offset:4096
	ds_read_b128 v[198:201], v135 offset:36864
	s_mov_b64 s[0:1], 0x30000
	v_lshl_add_u64 v[210:211], v[128:129], 0, s[0:1]
	s_waitcnt lgkmcnt(0)
	v_mfma_f32_32x32x16_bf16 v[96:111], v[186:189], v[190:193], v[96:111]
	v_mfma_f32_32x32x16_bf16 v[64:79], v[186:189], v[194:197], v[64:79]
	ds_read_b128 v[186:189], v135 offset:40960
	v_mfma_f32_32x32x16_bf16 v[112:127], v[198:201], v[190:193], v[112:127]
	v_mfma_f32_32x32x16_bf16 v[80:95], v[198:201], v[194:197], v[80:95]
	ds_read_b128 v[198:201], v135 offset:45056
	s_waitcnt lgkmcnt(0)
	v_mfma_f32_32x32x16_bf16 v[48:63], v[186:189], v[190:193], v[48:63]
	v_mfma_f32_32x32x16_bf16 v[16:31], v[186:189], v[194:197], v[16:31]
	ds_read_b128 v[186:189], v134 offset:32768
	v_mfma_f32_32x32x16_bf16 v[32:47], v[198:201], v[190:193], v[32:47]
	ds_read_b128 v[190:193], v139
	v_mfma_f32_32x32x16_bf16 v[0:15], v[198:201], v[194:197], v[0:15]
	ds_read_b128 v[194:197], v139 offset:4096
	ds_read_b128 v[198:201], v134 offset:36864
	s_waitcnt lgkmcnt(0)
	v_mfma_f32_32x32x16_bf16 v[96:111], v[186:189], v[190:193], v[96:111]
	v_mfma_f32_32x32x16_bf16 v[64:79], v[186:189], v[194:197], v[64:79]
	ds_read_b128 v[186:189], v134 offset:40960
	v_mfma_f32_32x32x16_bf16 v[112:127], v[198:201], v[190:193], v[112:127]
	v_mfma_f32_32x32x16_bf16 v[80:95], v[198:201], v[194:197], v[80:95]
	ds_read_b128 v[198:201], v134 offset:45056
	s_waitcnt vmcnt(0)
	s_barrier
; #define MFMA(a, b, c) __builtin_amdgcn_mfma_f32_32x32x16_bf16((a), (b), (c), 0, 0, 0)
;     ...
;     const bool pre = (kt + DIST < nk);
;     const char* base = smem + (kt % NSTG) * STAGE;
;     const char* pa = base + (wrow_act + r) * 128;
;     const char* pw = base + ABYTES + (wrow_w + r) * 128;
;     constexpr int NM = NI * MJ;
;     constexpr int PPS = (NLD + 1) / 2;
; #pragma unroll
;     for (int s = 0; s < 4; ++s) {
;       bf16x8 af[MJ], wf[NI];
; #pragma unroll
;       for (int j = 0; j < MJ; ++j) af[j] = *(const bf16x8*)(pa + j * 32 * 128 + xo[s]);
; #pragma unroll
;       for (int i = 0; i < NI; ++i) wf[i] = *(const bf16x8*)(pw + i * 32 * 128 + xo[s]);
; #pragma unroll
;       for (int m = 0; m < NM; ++m) {
;         const int i = m / MJ, j = m % MJ;
;         acc[i][j] = MFMA(wf[i], af[j], acc[i][j]);
;         if (s < 2 && NM >= PPS) {
;           constexpr int EVERY = (NM / PPS) > 0 ? (NM / PPS) : 1;
;           if ((m + 1) % EVERY == 0) {
;             const int pc = s * PPS + (m + 1) / EVERY - 1;
;             if ((m + 1) / EVERY <= PPS && pc < NLD) {
;               __builtin_amdgcn_sched_barrier(0);
;               if (pre) issue_piece(kt + DIST, pc);
;               __builtin_amdgcn_sched_barrier(0);
;             }
;           }
;         }
;         if (s < 2 && NM < PPS) {
;           const int slot = s * NM + m;
;           __builtin_amdgcn_sched_barrier(0);
; #pragma unroll
;           for (int pc = 0; pc < NLD; ++pc)
;             if ((pc * 2 * NM) / NLD == slot && pre) issue_piece(kt + DIST, pc);
;           __builtin_amdgcn_sched_barrier(0);
;         }
;       }
;     }
	s_waitcnt lgkmcnt(0)
	v_mfma_f32_32x32x16_bf16 v[48:63], v[186:189], v[190:193], v[48:63]
	v_mfma_f32_32x32x16_bf16 v[16:31], v[186:189], v[194:197], v[16:31]
	ds_read_b128 v[186:189], v138
	v_mfma_f32_32x32x16_bf16 v[32:47], v[198:201], v[190:193], v[32:47]
	ds_read_b128 v[190:193], v142
	v_mfma_f32_32x32x16_bf16 v[0:15], v[198:201], v[194:197], v[0:15]
	ds_read_b128 v[194:197], v142 offset:4096
	ds_read_b128 v[198:201], v138 offset:4096
	ds_read_b128 v[202:205], v138 offset:8192
	ds_read_b128 v[206:209], v138 offset:12288
	s_waitcnt lgkmcnt(0)
	v_mfma_f32_32x32x16_bf16 v[96:111], v[186:189], v[190:193], v[96:111]
	v_mfma_f32_32x32x16_bf16 v[64:79], v[186:189], v[194:197], v[64:79]
	v_lshl_add_u64 v[186:187], v[130:131], 0, s[0:1]
	v_readfirstlane_b32 s0, v184
	s_mov_b32 m0, s0
	s_nop 0
	global_load_lds_dwordx4 v[186:187], off
	v_mfma_f32_32x32x16_bf16 v[112:127], v[198:201], v[190:193], v[112:127]
	v_mfma_f32_32x32x16_bf16 v[80:95], v[198:201], v[194:197], v[80:95]
	s_mov_b64 s[6:7], 0x32000
	v_readfirstlane_b32 s1, v183
	v_lshl_add_u64 v[186:187], v[130:131], 0, s[6:7]
	s_mov_b32 m0, s1
	s_nop 0
	global_load_lds_dwordx4 v[186:187], off
	v_mfma_f32_32x32x16_bf16 v[48:63], v[202:205], v[190:193], v[48:63]
	v_mfma_f32_32x32x16_bf16 v[16:31], v[202:205], v[194:197], v[16:31]
	s_mov_b64 s[8:9], 0x34000
	v_readfirstlane_b32 s2, v182
	v_lshl_add_u64 v[186:187], v[130:131], 0, s[8:9]
	s_mov_b32 m0, s2
	s_nop 0
	global_load_lds_dwordx4 v[186:187], off
	v_mfma_f32_32x32x16_bf16 v[32:47], v[206:209], v[190:193], v[32:47]
	v_mfma_f32_32x32x16_bf16 v[0:15], v[206:209], v[194:197], v[0:15]
	s_mov_b64 s[10:11], 0x36000
	v_readfirstlane_b32 s3, v181
	v_lshl_add_u64 v[186:187], v[130:131], 0, s[10:11]
	s_mov_b32 m0, s3
	s_nop 0
	global_load_lds_dwordx4 v[186:187], off
	ds_read_b128 v[186:189], v144
	ds_read_b128 v[190:193], v151
	ds_read_b128 v[194:197], v151 offset:4096
	ds_read_b128 v[198:201], v144 offset:4096
	ds_read_b128 v[202:205], v144 offset:8192
	ds_read_b128 v[206:209], v144 offset:12288
	s_waitcnt lgkmcnt(0)
	v_mfma_f32_32x32x16_bf16 v[96:111], v[186:189], v[190:193], v[96:111]
	v_mfma_f32_32x32x16_bf16 v[64:79], v[186:189], v[194:197], v[64:79]
	v_readfirstlane_b32 s4, v162
	s_mov_b32 m0, s4
	s_nop 0
	global_load_lds_dwordx4 v[210:211], off
	v_mfma_f32_32x32x16_bf16 v[112:127], v[198:201], v[190:193], v[112:127]
	v_mfma_f32_32x32x16_bf16 v[80:95], v[198:201], v[194:197], v[80:95]
	v_readfirstlane_b32 s5, v165
	v_lshl_add_u64 v[186:187], v[128:129], 0, s[6:7]
	s_mov_b32 m0, s5
	s_nop 0
	global_load_lds_dwordx4 v[186:187], off
	v_mfma_f32_32x32x16_bf16 v[48:63], v[202:205], v[190:193], v[48:63]
	v_mfma_f32_32x32x16_bf16 v[16:31], v[202:205], v[194:197], v[16:31]
	v_readfirstlane_b32 s6, v164
	v_lshl_add_u64 v[186:187], v[128:129], 0, s[8:9]
	s_mov_b32 m0, s6
	s_nop 0
	global_load_lds_dwordx4 v[186:187], off
	v_mfma_f32_32x32x16_bf16 v[32:47], v[206:209], v[190:193], v[32:47]
	v_mfma_f32_32x32x16_bf16 v[0:15], v[206:209], v[194:197], v[0:15]
	v_readfirstlane_b32 s7, v163
	v_lshl_add_u64 v[186:187], v[128:129], 0, s[10:11]
	s_mov_b32 m0, s7
	s_nop 0
	global_load_lds_dwordx4 v[186:187], off
	ds_read_b128 v[186:189], v143
	ds_read_b128 v[190:193], v153
	ds_read_b128 v[194:197], v153 offset:4096
	ds_read_b128 v[198:201], v143 offset:4096
	s_mov_b64 s[8:9], 0x38000
	v_lshl_add_u64 v[210:211], v[128:129], 0, s[8:9]
	s_waitcnt lgkmcnt(0)
	v_mfma_f32_32x32x16_bf16 v[96:111], v[186:189], v[190:193], v[96:111]
	v_mfma_f32_32x32x16_bf16 v[64:79], v[186:189], v[194:197], v[64:79]
	ds_read_b128 v[186:189], v143 offset:8192
	v_mfma_f32_32x32x16_bf16 v[112:127], v[198:201], v[190:193], v[112:127]
	v_mfma_f32_32x32x16_bf16 v[80:95], v[198:201], v[194:197], v[80:95]
	ds_read_b128 v[198:201], v143 offset:12288
	s_waitcnt lgkmcnt(0)
	v_mfma_f32_32x32x16_bf16 v[48:63], v[186:189], v[190:193], v[48:63]
	v_mfma_f32_32x32x16_bf16 v[16:31], v[186:189], v[194:197], v[16:31]
	ds_read_b128 v[186:189], v141
	v_mfma_f32_32x32x16_bf16 v[32:47], v[198:201], v[190:193], v[32:47]
	ds_read_b128 v[190:193], v152
	v_mfma_f32_32x32x16_bf16 v[0:15], v[198:201], v[194:197], v[0:15]
	ds_read_b128 v[194:197], v152 offset:4096
	ds_read_b128 v[198:201], v141 offset:4096
	s_waitcnt lgkmcnt(0)
	v_mfma_f32_32x32x16_bf16 v[96:111], v[186:189], v[190:193], v[96:111]
	v_mfma_f32_32x32x16_bf16 v[64:79], v[186:189], v[194:197], v[64:79]
	ds_read_b128 v[186:189], v141 offset:8192
	v_mfma_f32_32x32x16_bf16 v[112:127], v[198:201], v[190:193], v[112:127]
	v_mfma_f32_32x32x16_bf16 v[80:95], v[198:201], v[194:197], v[80:95]
	ds_read_b128 v[198:201], v141 offset:12288
	s_waitcnt vmcnt(0)
	s_barrier
; #define MFMA(a, b, c) __builtin_amdgcn_mfma_f32_32x32x16_bf16((a), (b), (c), 0, 0, 0)
;     ...
;     const bool pre = (kt + DIST < nk);
;     const char* base = smem + (kt % NSTG) * STAGE;
;     const char* pa = base + (wrow_act + r) * 128;
;     const char* pw = base + ABYTES + (wrow_w + r) * 128;
;     constexpr int NM = NI * MJ;
;     constexpr int PPS = (NLD + 1) / 2;
; #pragma unroll
;     for (int s = 0; s < 4; ++s) {
;       bf16x8 af[MJ], wf[NI];
; #pragma unroll
;       for (int j = 0; j < MJ; ++j) af[j] = *(const bf16x8*)(pa + j * 32 * 128 + xo[s]);
; #pragma unroll
;       for (int i = 0; i < NI; ++i) wf[i] = *(const bf16x8*)(pw + i * 32 * 128 + xo[s]);
; #pragma unroll
;       for (int m = 0; m < NM; ++m) {
;         const int i = m / MJ, j = m % MJ;
;         acc[i][j] = MFMA(wf[i], af[j], acc[i][j]);
;         if (s < 2 && NM >= PPS) {
;           constexpr int EVERY = (NM / PPS) > 0 ? (NM / PPS) : 1;
;           if ((m + 1) % EVERY == 0) {
;             const int pc = s * PPS + (m + 1) / EVERY - 1;
;             if ((m + 1) / EVERY <= PPS && pc < NLD) {
;               __builtin_amdgcn_sched_barrier(0);
;               if (pre) issue_piece(kt + DIST, pc);
;               __builtin_amdgcn_sched_barrier(0);
;             }
;           }
;         }
;         if (s < 2 && NM < PPS) {
;           const int slot = s * NM + m;
;           __builtin_amdgcn_sched_barrier(0);
; #pragma unroll
;           for (int pc = 0; pc < NLD; ++pc)
;             if ((pc * 2 * NM) / NLD == slot && pre) issue_piece(kt + DIST, pc);
;           __builtin_amdgcn_sched_barrier(0);
;         }
;       }
;     }
	s_waitcnt lgkmcnt(0)
	v_mfma_f32_32x32x16_bf16 v[48:63], v[186:189], v[190:193], v[48:63]
	v_mfma_f32_32x32x16_bf16 v[16:31], v[186:189], v[194:197], v[16:31]
	ds_read_b128 v[186:189], v132 offset:32768
	v_mfma_f32_32x32x16_bf16 v[32:47], v[198:201], v[190:193], v[32:47]
	ds_read_b128 v[190:193], v136
	v_mfma_f32_32x32x16_bf16 v[0:15], v[198:201], v[194:197], v[0:15]
	ds_read_b128 v[194:197], v136 offset:4096
	ds_read_b128 v[198:201], v132 offset:36864
	ds_read_b128 v[202:205], v132 offset:40960
	ds_read_b128 v[206:209], v132 offset:45056
	s_waitcnt lgkmcnt(0)
	v_mfma_f32_32x32x16_bf16 v[96:111], v[186:189], v[190:193], v[96:111]
	v_mfma_f32_32x32x16_bf16 v[64:79], v[186:189], v[194:197], v[64:79]
	v_lshl_add_u64 v[186:187], v[130:131], 0, s[8:9]
	v_readfirstlane_b32 s8, v155
	s_mov_b32 m0, s8
	s_nop 0
	global_load_lds_dwordx4 v[186:187], off
	v_mfma_f32_32x32x16_bf16 v[112:127], v[198:201], v[190:193], v[112:127]
	v_mfma_f32_32x32x16_bf16 v[80:95], v[198:201], v[194:197], v[80:95]
	s_mov_b64 s[14:15], 0x3a000
	v_readfirstlane_b32 s9, v158
	v_lshl_add_u64 v[186:187], v[130:131], 0, s[14:15]
	s_mov_b32 m0, s9
	s_nop 0
	global_load_lds_dwordx4 v[186:187], off
	v_mfma_f32_32x32x16_bf16 v[48:63], v[202:205], v[190:193], v[48:63]
	v_mfma_f32_32x32x16_bf16 v[16:31], v[202:205], v[194:197], v[16:31]
	s_mov_b64 s[16:17], 0x3c000
	v_readfirstlane_b32 s10, v157
	v_lshl_add_u64 v[186:187], v[130:131], 0, s[16:17]
	s_mov_b32 m0, s10
	s_nop 0
	global_load_lds_dwordx4 v[186:187], off
	v_mfma_f32_32x32x16_bf16 v[32:47], v[206:209], v[190:193], v[32:47]
	v_mfma_f32_32x32x16_bf16 v[0:15], v[206:209], v[194:197], v[0:15]
	s_mov_b64 s[18:19], 0x3e000
	v_readfirstlane_b32 s11, v156
	v_lshl_add_u64 v[186:187], v[130:131], 0, s[18:19]
	s_mov_b32 m0, s11
	s_nop 0
	global_load_lds_dwordx4 v[186:187], off
	ds_read_b128 v[186:189], v133 offset:32768
	ds_read_b128 v[190:193], v137
	ds_read_b128 v[194:197], v137 offset:4096
	ds_read_b128 v[198:201], v133 offset:36864
	ds_read_b128 v[202:205], v133 offset:40960
	ds_read_b128 v[206:209], v133 offset:45056
	s_waitcnt lgkmcnt(0)
	v_mfma_f32_32x32x16_bf16 v[96:111], v[186:189], v[190:193], v[96:111]
	v_mfma_f32_32x32x16_bf16 v[64:79], v[186:189], v[194:197], v[64:79]
	v_readfirstlane_b32 s12, v154
	s_mov_b32 m0, s12
	s_nop 0
	global_load_lds_dwordx4 v[210:211], off
	v_mfma_f32_32x32x16_bf16 v[112:127], v[198:201], v[190:193], v[112:127]
	v_mfma_f32_32x32x16_bf16 v[80:95], v[198:201], v[194:197], v[80:95]
	v_readfirstlane_b32 s13, v159
	v_lshl_add_u64 v[186:187], v[128:129], 0, s[14:15]
	s_mov_b32 m0, s13
	s_nop 0
	global_load_lds_dwordx4 v[186:187], off
	v_mfma_f32_32x32x16_bf16 v[48:63], v[202:205], v[190:193], v[48:63]
	v_mfma_f32_32x32x16_bf16 v[16:31], v[202:205], v[194:197], v[16:31]
	v_readfirstlane_b32 s14, v160
	v_lshl_add_u64 v[186:187], v[128:129], 0, s[16:17]
	s_mov_b32 m0, s14
	s_nop 0
	global_load_lds_dwordx4 v[186:187], off
	v_mfma_f32_32x32x16_bf16 v[32:47], v[206:209], v[190:193], v[32:47]
	v_mfma_f32_32x32x16_bf16 v[0:15], v[206:209], v[194:197], v[0:15]
	v_readfirstlane_b32 s15, v161
	v_lshl_add_u64 v[186:187], v[128:129], 0, s[18:19]
	s_mov_b32 m0, s15
	s_nop 0
	global_load_lds_dwordx4 v[186:187], off
	ds_read_b128 v[186:189], v135 offset:32768
	ds_read_b128 v[190:193], v140
	ds_read_b128 v[194:197], v140 offset:4096
	ds_read_b128 v[198:201], v135 offset:36864
	s_mov_b64 s[16:17], 0x40000
	v_lshl_add_u64 v[210:211], v[128:129], 0, s[16:17]
	s_waitcnt lgkmcnt(0)
	v_mfma_f32_32x32x16_bf16 v[96:111], v[186:189], v[190:193], v[96:111]
	v_mfma_f32_32x32x16_bf16 v[64:79], v[186:189], v[194:197], v[64:79]
	ds_read_b128 v[186:189], v135 offset:40960
	v_mfma_f32_32x32x16_bf16 v[112:127], v[198:201], v[190:193], v[112:127]
	v_mfma_f32_32x32x16_bf16 v[80:95], v[198:201], v[194:197], v[80:95]
	ds_read_b128 v[198:201], v135 offset:45056
	s_waitcnt lgkmcnt(0)
	v_mfma_f32_32x32x16_bf16 v[48:63], v[186:189], v[190:193], v[48:63]
	v_mfma_f32_32x32x16_bf16 v[16:31], v[186:189], v[194:197], v[16:31]
	ds_read_b128 v[186:189], v134 offset:32768
	v_mfma_f32_32x32x16_bf16 v[32:47], v[198:201], v[190:193], v[32:47]
	ds_read_b128 v[190:193], v139
	v_mfma_f32_32x32x16_bf16 v[0:15], v[198:201], v[194:197], v[0:15]
	ds_read_b128 v[194:197], v139 offset:4096
	ds_read_b128 v[198:201], v134 offset:36864
	s_waitcnt lgkmcnt(0)
	v_mfma_f32_32x32x16_bf16 v[96:111], v[186:189], v[190:193], v[96:111]
	v_mfma_f32_32x32x16_bf16 v[64:79], v[186:189], v[194:197], v[64:79]
	ds_read_b128 v[186:189], v134 offset:40960
	v_mfma_f32_32x32x16_bf16 v[112:127], v[198:201], v[190:193], v[112:127]
	v_mfma_f32_32x32x16_bf16 v[80:95], v[198:201], v[194:197], v[80:95]
	ds_read_b128 v[198:201], v134 offset:45056
	s_waitcnt vmcnt(0)
	s_barrier
; #define MFMA(a, b, c) __builtin_amdgcn_mfma_f32_32x32x16_bf16((a), (b), (c), 0, 0, 0)
;     ...
;     const bool pre = (kt + DIST < nk);
;     const char* base = smem + (kt % NSTG) * STAGE;
;     const char* pa = base + (wrow_act + r) * 128;
;     const char* pw = base + ABYTES + (wrow_w + r) * 128;
;     constexpr int NM = NI * MJ;
;     constexpr int PPS = (NLD + 1) / 2;
; #pragma unroll
;     for (int s = 0; s < 4; ++s) {
;       bf16x8 af[MJ], wf[NI];
; #pragma unroll
;       for (int j = 0; j < MJ; ++j) af[j] = *(const bf16x8*)(pa + j * 32 * 128 + xo[s]);
; #pragma unroll
;       for (int i = 0; i < NI; ++i) wf[i] = *(const bf16x8*)(pw + i * 32 * 128 + xo[s]);
; #pragma unroll
;       for (int m = 0; m < NM; ++m) {
;         const int i = m / MJ, j = m % MJ;
;         acc[i][j] = MFMA(wf[i], af[j], acc[i][j]);
;         if (s < 2 && NM >= PPS) {
;           constexpr int EVERY = (NM / PPS) > 0 ? (NM / PPS) : 1;
;           if ((m + 1) % EVERY == 0) {
;             const int pc = s * PPS + (m + 1) / EVERY - 1;
;             if ((m + 1) / EVERY <= PPS && pc < NLD) {
;               __builtin_amdgcn_sched_barrier(0);
;               if (pre) issue_piece(kt + DIST, pc);
;               __builtin_amdgcn_sched_barrier(0);
;             }
;           }
;         }
;         if (s < 2 && NM < PPS) {
;           const int slot = s * NM + m;
;           __builtin_amdgcn_sched_barrier(0);
; #pragma unroll
;           for (int pc = 0; pc < NLD; ++pc)
;             if ((pc * 2 * NM) / NLD == slot && pre) issue_piece(kt + DIST, pc);
;           __builtin_amdgcn_sched_barrier(0);
;         }
;       }
;     }
	s_waitcnt lgkmcnt(0)
	v_mfma_f32_32x32x16_bf16 v[48:63], v[186:189], v[190:193], v[48:63]
	v_mfma_f32_32x32x16_bf16 v[16:31], v[186:189], v[194:197], v[16:31]
	ds_read_b128 v[186:189], v138
	v_mfma_f32_32x32x16_bf16 v[32:47], v[198:201], v[190:193], v[32:47]
	ds_read_b128 v[190:193], v142
	v_mfma_f32_32x32x16_bf16 v[0:15], v[198:201], v[194:197], v[0:15]
	ds_read_b128 v[194:197], v142 offset:4096
	ds_read_b128 v[198:201], v138 offset:4096
	ds_read_b128 v[202:205], v138 offset:8192
	ds_read_b128 v[206:209], v138 offset:12288
	s_waitcnt lgkmcnt(0)
	v_mfma_f32_32x32x16_bf16 v[96:111], v[186:189], v[190:193], v[96:111]
	v_mfma_f32_32x32x16_bf16 v[64:79], v[186:189], v[194:197], v[64:79]
	v_lshl_add_u64 v[186:187], v[130:131], 0, s[16:17]
	s_mov_b32 m0, s0
	s_nop 0
	global_load_lds_dwordx4 v[186:187], off
	v_mfma_f32_32x32x16_bf16 v[112:127], v[198:201], v[190:193], v[112:127]
	v_mfma_f32_32x32x16_bf16 v[80:95], v[198:201], v[194:197], v[80:95]
	s_mov_b64 s[16:17], 0x42000
	v_lshl_add_u64 v[186:187], v[130:131], 0, s[16:17]
	s_mov_b32 m0, s1
	s_nop 0
	global_load_lds_dwordx4 v[186:187], off
	v_mfma_f32_32x32x16_bf16 v[48:63], v[202:205], v[190:193], v[48:63]
	v_mfma_f32_32x32x16_bf16 v[16:31], v[202:205], v[194:197], v[16:31]
	s_mov_b64 s[18:19], 0x44000
	v_lshl_add_u64 v[186:187], v[130:131], 0, s[18:19]
	s_mov_b32 m0, s2
	s_nop 0
	global_load_lds_dwordx4 v[186:187], off
	v_mfma_f32_32x32x16_bf16 v[32:47], v[206:209], v[190:193], v[32:47]
	v_mfma_f32_32x32x16_bf16 v[0:15], v[206:209], v[194:197], v[0:15]
	s_mov_b64 s[20:21], 0x46000
	v_lshl_add_u64 v[186:187], v[130:131], 0, s[20:21]
	s_mov_b32 m0, s3
	s_nop 0
	global_load_lds_dwordx4 v[186:187], off
	ds_read_b128 v[186:189], v144
	ds_read_b128 v[190:193], v151
	ds_read_b128 v[194:197], v151 offset:4096
	ds_read_b128 v[198:201], v144 offset:4096
	ds_read_b128 v[202:205], v144 offset:8192
	ds_read_b128 v[206:209], v144 offset:12288
	s_waitcnt lgkmcnt(0)
	v_mfma_f32_32x32x16_bf16 v[96:111], v[186:189], v[190:193], v[96:111]
	v_mfma_f32_32x32x16_bf16 v[64:79], v[186:189], v[194:197], v[64:79]
	s_mov_b32 m0, s4
	s_nop 0
	global_load_lds_dwordx4 v[210:211], off
	v_mfma_f32_32x32x16_bf16 v[112:127], v[198:201], v[190:193], v[112:127]
	v_mfma_f32_32x32x16_bf16 v[80:95], v[198:201], v[194:197], v[80:95]
	v_lshl_add_u64 v[186:187], v[128:129], 0, s[16:17]
	s_mov_b32 m0, s5
	s_nop 0
	global_load_lds_dwordx4 v[186:187], off
	v_mfma_f32_32x32x16_bf16 v[48:63], v[202:205], v[190:193], v[48:63]
	v_mfma_f32_32x32x16_bf16 v[16:31], v[202:205], v[194:197], v[16:31]
	v_lshl_add_u64 v[186:187], v[128:129], 0, s[18:19]
	s_mov_b32 m0, s6
	s_nop 0
	global_load_lds_dwordx4 v[186:187], off
	v_mfma_f32_32x32x16_bf16 v[32:47], v[206:209], v[190:193], v[32:47]
	v_mfma_f32_32x32x16_bf16 v[0:15], v[206:209], v[194:197], v[0:15]
	v_lshl_add_u64 v[186:187], v[128:129], 0, s[20:21]
	s_mov_b32 m0, s7
	s_nop 0
	global_load_lds_dwordx4 v[186:187], off
	ds_read_b128 v[186:189], v143
	ds_read_b128 v[190:193], v153
	ds_read_b128 v[194:197], v153 offset:4096
	ds_read_b128 v[198:201], v143 offset:4096
	s_mov_b64 s[16:17], 0x48000
	v_lshl_add_u64 v[210:211], v[128:129], 0, s[16:17]
	s_waitcnt lgkmcnt(0)
	v_mfma_f32_32x32x16_bf16 v[96:111], v[186:189], v[190:193], v[96:111]
	v_mfma_f32_32x32x16_bf16 v[64:79], v[186:189], v[194:197], v[64:79]
	ds_read_b128 v[186:189], v143 offset:8192
	v_mfma_f32_32x32x16_bf16 v[112:127], v[198:201], v[190:193], v[112:127]
	v_mfma_f32_32x32x16_bf16 v[80:95], v[198:201], v[194:197], v[80:95]
	ds_read_b128 v[198:201], v143 offset:12288
	s_waitcnt lgkmcnt(0)
	v_mfma_f32_32x32x16_bf16 v[48:63], v[186:189], v[190:193], v[48:63]
	v_mfma_f32_32x32x16_bf16 v[16:31], v[186:189], v[194:197], v[16:31]
	ds_read_b128 v[186:189], v141
	v_mfma_f32_32x32x16_bf16 v[32:47], v[198:201], v[190:193], v[32:47]
	ds_read_b128 v[190:193], v152
	v_mfma_f32_32x32x16_bf16 v[0:15], v[198:201], v[194:197], v[0:15]
	ds_read_b128 v[194:197], v152 offset:4096
	ds_read_b128 v[198:201], v141 offset:4096
	s_waitcnt lgkmcnt(0)
	v_mfma_f32_32x32x16_bf16 v[96:111], v[186:189], v[190:193], v[96:111]
	v_mfma_f32_32x32x16_bf16 v[64:79], v[186:189], v[194:197], v[64:79]
	ds_read_b128 v[186:189], v141 offset:8192
	v_mfma_f32_32x32x16_bf16 v[112:127], v[198:201], v[190:193], v[112:127]
	v_mfma_f32_32x32x16_bf16 v[80:95], v[198:201], v[194:197], v[80:95]
	ds_read_b128 v[198:201], v141 offset:12288
	s_waitcnt vmcnt(0)
	s_barrier
; #define MFMA(a, b, c) __builtin_amdgcn_mfma_f32_32x32x16_bf16((a), (b), (c), 0, 0, 0)
;     ...
;     const bool pre = (kt + DIST < nk);
;     const char* base = smem + (kt % NSTG) * STAGE;
;     const char* pa = base + (wrow_act + r) * 128;
;     const char* pw = base + ABYTES + (wrow_w + r) * 128;
;     constexpr int NM = NI * MJ;
;     constexpr int PPS = (NLD + 1) / 2;
; #pragma unroll
;     for (int s = 0; s < 4; ++s) {
;       bf16x8 af[MJ], wf[NI];
; #pragma unroll
;       for (int j = 0; j < MJ; ++j) af[j] = *(const bf16x8*)(pa + j * 32 * 128 + xo[s]);
; #pragma unroll
;       for (int i = 0; i < NI; ++i) wf[i] = *(const bf16x8*)(pw + i * 32 * 128 + xo[s]);
; #pragma unroll
;       for (int m = 0; m < NM; ++m) {
;         const int i = m / MJ, j = m % MJ;
;         acc[i][j] = MFMA(wf[i], af[j], acc[i][j]);
;         if (s < 2 && NM >= PPS) {
;           constexpr int EVERY = (NM / PPS) > 0 ? (NM / PPS) : 1;
;           if ((m + 1) % EVERY == 0) {
;             const int pc = s * PPS + (m + 1) / EVERY - 1;
;             if ((m + 1) / EVERY <= PPS && pc < NLD) {
;               __builtin_amdgcn_sched_barrier(0);
;               if (pre) issue_piece(kt + DIST, pc);
;               __builtin_amdgcn_sched_barrier(0);
;             }
;           }
;         }
;         if (s < 2 && NM < PPS) {
;           const int slot = s * NM + m;
;           __builtin_amdgcn_sched_barrier(0);
; #pragma unroll
;           for (int pc = 0; pc < NLD; ++pc)
;             if ((pc * 2 * NM) / NLD == slot && pre) issue_piece(kt + DIST, pc);
;           __builtin_amdgcn_sched_barrier(0);
;         }
;       }
;     }
	s_waitcnt lgkmcnt(0)
	v_mfma_f32_32x32x16_bf16 v[48:63], v[186:189], v[190:193], v[48:63]
	v_mfma_f32_32x32x16_bf16 v[16:31], v[186:189], v[194:197], v[16:31]
	ds_read_b128 v[186:189], v132 offset:32768
	v_mfma_f32_32x32x16_bf16 v[32:47], v[198:201], v[190:193], v[32:47]
	ds_read_b128 v[190:193], v136
	v_mfma_f32_32x32x16_bf16 v[0:15], v[198:201], v[194:197], v[0:15]
	ds_read_b128 v[194:197], v136 offset:4096
	ds_read_b128 v[198:201], v132 offset:36864
	ds_read_b128 v[202:205], v132 offset:40960
	ds_read_b128 v[206:209], v132 offset:45056
	s_waitcnt lgkmcnt(0)
	v_mfma_f32_32x32x16_bf16 v[96:111], v[186:189], v[190:193], v[96:111]
	v_mfma_f32_32x32x16_bf16 v[64:79], v[186:189], v[194:197], v[64:79]
	v_lshl_add_u64 v[186:187], v[130:131], 0, s[16:17]
	s_mov_b32 m0, s8
	s_nop 0
	global_load_lds_dwordx4 v[186:187], off
	v_mfma_f32_32x32x16_bf16 v[112:127], v[198:201], v[190:193], v[112:127]
	v_mfma_f32_32x32x16_bf16 v[80:95], v[198:201], v[194:197], v[80:95]
	s_mov_b64 s[16:17], 0x4a000
	v_lshl_add_u64 v[186:187], v[130:131], 0, s[16:17]
	s_mov_b32 m0, s9
	s_nop 0
	global_load_lds_dwordx4 v[186:187], off
	v_mfma_f32_32x32x16_bf16 v[48:63], v[202:205], v[190:193], v[48:63]
	v_mfma_f32_32x32x16_bf16 v[16:31], v[202:205], v[194:197], v[16:31]
	s_mov_b64 s[18:19], 0x4c000
	v_lshl_add_u64 v[186:187], v[130:131], 0, s[18:19]
	s_mov_b32 m0, s10
	s_nop 0
	global_load_lds_dwordx4 v[186:187], off
	v_mfma_f32_32x32x16_bf16 v[32:47], v[206:209], v[190:193], v[32:47]
	v_mfma_f32_32x32x16_bf16 v[0:15], v[206:209], v[194:197], v[0:15]
	s_mov_b64 s[20:21], 0x4e000
	v_lshl_add_u64 v[186:187], v[130:131], 0, s[20:21]
	s_mov_b32 m0, s11
	s_nop 0
	global_load_lds_dwordx4 v[186:187], off
	ds_read_b128 v[186:189], v133 offset:32768
	ds_read_b128 v[190:193], v137
	ds_read_b128 v[194:197], v137 offset:4096
	ds_read_b128 v[198:201], v133 offset:36864
	ds_read_b128 v[202:205], v133 offset:40960
	ds_read_b128 v[206:209], v133 offset:45056
	s_waitcnt lgkmcnt(0)
	v_mfma_f32_32x32x16_bf16 v[96:111], v[186:189], v[190:193], v[96:111]
	v_mfma_f32_32x32x16_bf16 v[64:79], v[186:189], v[194:197], v[64:79]
	s_mov_b32 m0, s12
	s_nop 0
	global_load_lds_dwordx4 v[210:211], off
	v_mfma_f32_32x32x16_bf16 v[112:127], v[198:201], v[190:193], v[112:127]
	v_mfma_f32_32x32x16_bf16 v[80:95], v[198:201], v[194:197], v[80:95]
	v_lshl_add_u64 v[186:187], v[128:129], 0, s[16:17]
	s_mov_b32 m0, s13
	s_nop 0
	global_load_lds_dwordx4 v[186:187], off
	v_mfma_f32_32x32x16_bf16 v[48:63], v[202:205], v[190:193], v[48:63]
	v_mfma_f32_32x32x16_bf16 v[16:31], v[202:205], v[194:197], v[16:31]
	v_lshl_add_u64 v[186:187], v[128:129], 0, s[18:19]
	s_mov_b32 m0, s14
	s_nop 0
	global_load_lds_dwordx4 v[186:187], off
	v_mfma_f32_32x32x16_bf16 v[32:47], v[206:209], v[190:193], v[32:47]
	v_mfma_f32_32x32x16_bf16 v[0:15], v[206:209], v[194:197], v[0:15]
	v_lshl_add_u64 v[186:187], v[128:129], 0, s[20:21]
	s_mov_b32 m0, s15
	s_nop 0
	global_load_lds_dwordx4 v[186:187], off
	ds_read_b128 v[186:189], v135 offset:32768
	ds_read_b128 v[190:193], v140
	ds_read_b128 v[194:197], v140 offset:4096
	ds_read_b128 v[198:201], v135 offset:36864
	s_mov_b64 s[16:17], 0x50000
	v_lshl_add_u64 v[210:211], v[128:129], 0, s[16:17]
	s_waitcnt lgkmcnt(0)
	v_mfma_f32_32x32x16_bf16 v[96:111], v[186:189], v[190:193], v[96:111]
	v_mfma_f32_32x32x16_bf16 v[64:79], v[186:189], v[194:197], v[64:79]
	ds_read_b128 v[186:189], v135 offset:40960
	v_mfma_f32_32x32x16_bf16 v[112:127], v[198:201], v[190:193], v[112:127]
	v_mfma_f32_32x32x16_bf16 v[80:95], v[198:201], v[194:197], v[80:95]
	ds_read_b128 v[198:201], v135 offset:45056
	s_waitcnt lgkmcnt(0)
	v_mfma_f32_32x32x16_bf16 v[48:63], v[186:189], v[190:193], v[48:63]
	v_mfma_f32_32x32x16_bf16 v[16:31], v[186:189], v[194:197], v[16:31]
	ds_read_b128 v[186:189], v134 offset:32768
	v_mfma_f32_32x32x16_bf16 v[32:47], v[198:201], v[190:193], v[32:47]
	ds_read_b128 v[190:193], v139
	v_mfma_f32_32x32x16_bf16 v[0:15], v[198:201], v[194:197], v[0:15]
	ds_read_b128 v[194:197], v139 offset:4096
	ds_read_b128 v[198:201], v134 offset:36864
	s_waitcnt lgkmcnt(0)
	v_mfma_f32_32x32x16_bf16 v[96:111], v[186:189], v[190:193], v[96:111]
	v_mfma_f32_32x32x16_bf16 v[64:79], v[186:189], v[194:197], v[64:79]
	ds_read_b128 v[186:189], v134 offset:40960
	v_mfma_f32_32x32x16_bf16 v[112:127], v[198:201], v[190:193], v[112:127]
	v_mfma_f32_32x32x16_bf16 v[80:95], v[198:201], v[194:197], v[80:95]
	ds_read_b128 v[198:201], v134 offset:45056
	s_waitcnt vmcnt(0)
	s_barrier
; #define MFMA(a, b, c) __builtin_amdgcn_mfma_f32_32x32x16_bf16((a), (b), (c), 0, 0, 0)
;     ...
;     const bool pre = (kt + DIST < nk);
;     const char* base = smem + (kt % NSTG) * STAGE;
;     const char* pa = base + (wrow_act + r) * 128;
;     const char* pw = base + ABYTES + (wrow_w + r) * 128;
;     constexpr int NM = NI * MJ;
;     constexpr int PPS = (NLD + 1) / 2;
; #pragma unroll
;     for (int s = 0; s < 4; ++s) {
;       bf16x8 af[MJ], wf[NI];
; #pragma unroll
;       for (int j = 0; j < MJ; ++j) af[j] = *(const bf16x8*)(pa + j * 32 * 128 + xo[s]);
; #pragma unroll
;       for (int i = 0; i < NI; ++i) wf[i] = *(const bf16x8*)(pw + i * 32 * 128 + xo[s]);
; #pragma unroll
;       for (int m = 0; m < NM; ++m) {
;         const int i = m / MJ, j = m % MJ;
;         acc[i][j] = MFMA(wf[i], af[j], acc[i][j]);
;         if (s < 2 && NM >= PPS) {
;           constexpr int EVERY = (NM / PPS) > 0 ? (NM / PPS) : 1;
;           if ((m + 1) % EVERY == 0) {
;             const int pc = s * PPS + (m + 1) / EVERY - 1;
;             if ((m + 1) / EVERY <= PPS && pc < NLD) {
;               __builtin_amdgcn_sched_barrier(0);
;               if (pre) issue_piece(kt + DIST, pc);
;               __builtin_amdgcn_sched_barrier(0);
;             }
;           }
;         }
;         if (s < 2 && NM < PPS) {
;           const int slot = s * NM + m;
;           __builtin_amdgcn_sched_barrier(0);
; #pragma unroll
;           for (int pc = 0; pc < NLD; ++pc)
;             if ((pc * 2 * NM) / NLD == slot && pre) issue_piece(kt + DIST, pc);
;           __builtin_amdgcn_sched_barrier(0);
;         }
;       }
;     }
	s_waitcnt lgkmcnt(0)
	v_mfma_f32_32x32x16_bf16 v[48:63], v[186:189], v[190:193], v[48:63]
	v_mfma_f32_32x32x16_bf16 v[16:31], v[186:189], v[194:197], v[16:31]
	ds_read_b128 v[186:189], v138
	v_mfma_f32_32x32x16_bf16 v[32:47], v[198:201], v[190:193], v[32:47]
	ds_read_b128 v[190:193], v142
	v_mfma_f32_32x32x16_bf16 v[0:15], v[198:201], v[194:197], v[0:15]
	ds_read_b128 v[194:197], v142 offset:4096
	ds_read_b128 v[198:201], v138 offset:4096
	ds_read_b128 v[202:205], v138 offset:8192
	ds_read_b128 v[206:209], v138 offset:12288
	s_waitcnt lgkmcnt(0)
	v_mfma_f32_32x32x16_bf16 v[96:111], v[186:189], v[190:193], v[96:111]
	v_mfma_f32_32x32x16_bf16 v[64:79], v[186:189], v[194:197], v[64:79]
	v_lshl_add_u64 v[186:187], v[130:131], 0, s[16:17]
	s_mov_b32 m0, s0
	s_nop 0
	global_load_lds_dwordx4 v[186:187], off
	v_mfma_f32_32x32x16_bf16 v[112:127], v[198:201], v[190:193], v[112:127]
	v_mfma_f32_32x32x16_bf16 v[80:95], v[198:201], v[194:197], v[80:95]
	s_mov_b64 s[16:17], 0x52000
	v_lshl_add_u64 v[186:187], v[130:131], 0, s[16:17]
	s_mov_b32 m0, s1
	s_nop 0
	global_load_lds_dwordx4 v[186:187], off
	v_mfma_f32_32x32x16_bf16 v[48:63], v[202:205], v[190:193], v[48:63]
	v_mfma_f32_32x32x16_bf16 v[16:31], v[202:205], v[194:197], v[16:31]
	s_mov_b64 s[0:1], 0x54000
	v_lshl_add_u64 v[186:187], v[130:131], 0, s[0:1]
	s_mov_b32 m0, s2
	s_nop 0
	global_load_lds_dwordx4 v[186:187], off
	v_mfma_f32_32x32x16_bf16 v[32:47], v[206:209], v[190:193], v[32:47]
	v_mfma_f32_32x32x16_bf16 v[0:15], v[206:209], v[194:197], v[0:15]
	s_mov_b64 s[18:19], 0x56000
	v_lshl_add_u64 v[186:187], v[130:131], 0, s[18:19]
	s_mov_b32 m0, s3
	s_nop 0
	global_load_lds_dwordx4 v[186:187], off
	ds_read_b128 v[186:189], v144
	ds_read_b128 v[190:193], v151
	ds_read_b128 v[194:197], v151 offset:4096
	ds_read_b128 v[198:201], v144 offset:4096
	ds_read_b128 v[202:205], v144 offset:8192
	ds_read_b128 v[206:209], v144 offset:12288
	s_waitcnt lgkmcnt(0)
	v_mfma_f32_32x32x16_bf16 v[96:111], v[186:189], v[190:193], v[96:111]
	v_mfma_f32_32x32x16_bf16 v[64:79], v[186:189], v[194:197], v[64:79]
	s_mov_b32 m0, s4
	s_nop 0
	global_load_lds_dwordx4 v[210:211], off
	v_mfma_f32_32x32x16_bf16 v[112:127], v[198:201], v[190:193], v[112:127]
	v_mfma_f32_32x32x16_bf16 v[80:95], v[198:201], v[194:197], v[80:95]
	v_lshl_add_u64 v[186:187], v[128:129], 0, s[16:17]
	s_mov_b32 m0, s5
	s_nop 0
	global_load_lds_dwordx4 v[186:187], off
	v_mfma_f32_32x32x16_bf16 v[48:63], v[202:205], v[190:193], v[48:63]
	v_mfma_f32_32x32x16_bf16 v[16:31], v[202:205], v[194:197], v[16:31]
	v_lshl_add_u64 v[186:187], v[128:129], 0, s[0:1]
	s_mov_b32 m0, s6
	s_nop 0
	global_load_lds_dwordx4 v[186:187], off
	v_mfma_f32_32x32x16_bf16 v[32:47], v[206:209], v[190:193], v[32:47]
	v_mfma_f32_32x32x16_bf16 v[0:15], v[206:209], v[194:197], v[0:15]
	v_lshl_add_u64 v[186:187], v[128:129], 0, s[18:19]
	s_mov_b32 m0, s7
	s_nop 0
	global_load_lds_dwordx4 v[186:187], off
	ds_read_b128 v[186:189], v143
	ds_read_b128 v[190:193], v153
	ds_read_b128 v[194:197], v153 offset:4096
	ds_read_b128 v[198:201], v143 offset:4096
	s_mov_b64 s[0:1], 0x58000
	v_lshl_add_u64 v[210:211], v[128:129], 0, s[0:1]
	s_waitcnt lgkmcnt(0)
	v_mfma_f32_32x32x16_bf16 v[96:111], v[186:189], v[190:193], v[96:111]
	v_mfma_f32_32x32x16_bf16 v[64:79], v[186:189], v[194:197], v[64:79]
	ds_read_b128 v[186:189], v143 offset:8192
	v_mfma_f32_32x32x16_bf16 v[112:127], v[198:201], v[190:193], v[112:127]
	v_mfma_f32_32x32x16_bf16 v[80:95], v[198:201], v[194:197], v[80:95]
	ds_read_b128 v[198:201], v143 offset:12288
	s_waitcnt lgkmcnt(0)
	v_mfma_f32_32x32x16_bf16 v[48:63], v[186:189], v[190:193], v[48:63]
	v_mfma_f32_32x32x16_bf16 v[16:31], v[186:189], v[194:197], v[16:31]
	ds_read_b128 v[186:189], v141
	v_mfma_f32_32x32x16_bf16 v[32:47], v[198:201], v[190:193], v[32:47]
	ds_read_b128 v[190:193], v152
	v_mfma_f32_32x32x16_bf16 v[0:15], v[198:201], v[194:197], v[0:15]
	ds_read_b128 v[194:197], v152 offset:4096
	ds_read_b128 v[198:201], v141 offset:4096
	s_waitcnt lgkmcnt(0)
	v_mfma_f32_32x32x16_bf16 v[96:111], v[186:189], v[190:193], v[96:111]
	v_mfma_f32_32x32x16_bf16 v[64:79], v[186:189], v[194:197], v[64:79]
	ds_read_b128 v[186:189], v141 offset:8192
	v_mfma_f32_32x32x16_bf16 v[112:127], v[198:201], v[190:193], v[112:127]
	v_mfma_f32_32x32x16_bf16 v[80:95], v[198:201], v[194:197], v[80:95]
	ds_read_b128 v[198:201], v141 offset:12288
	s_waitcnt vmcnt(0)
	s_barrier
; #define MFMA(a, b, c) __builtin_amdgcn_mfma_f32_32x32x16_bf16((a), (b), (c), 0, 0, 0)
;     ...
;     const bool pre = (kt + DIST < nk);
;     const char* base = smem + (kt % NSTG) * STAGE;
;     const char* pa = base + (wrow_act + r) * 128;
;     const char* pw = base + ABYTES + (wrow_w + r) * 128;
;     constexpr int NM = NI * MJ;
;     constexpr int PPS = (NLD + 1) / 2;
; #pragma unroll
;     for (int s = 0; s < 4; ++s) {
;       bf16x8 af[MJ], wf[NI];
; #pragma unroll
;       for (int j = 0; j < MJ; ++j) af[j] = *(const bf16x8*)(pa + j * 32 * 128 + xo[s]);
; #pragma unroll
;       for (int i = 0; i < NI; ++i) wf[i] = *(const bf16x8*)(pw + i * 32 * 128 + xo[s]);
; #pragma unroll
;       for (int m = 0; m < NM; ++m) {
;         const int i = m / MJ, j = m % MJ;
;         acc[i][j] = MFMA(wf[i], af[j], acc[i][j]);
;         if (s < 2 && NM >= PPS) {
;           constexpr int EVERY = (NM / PPS) > 0 ? (NM / PPS) : 1;
;           if ((m + 1) % EVERY == 0) {
;             const int pc = s * PPS + (m + 1) / EVERY - 1;
;             if ((m + 1) / EVERY <= PPS && pc < NLD) {
;               __builtin_amdgcn_sched_barrier(0);
;               if (pre) issue_piece(kt + DIST, pc);
;               __builtin_amdgcn_sched_barrier(0);
;             }
;           }
;         }
;         if (s < 2 && NM < PPS) {
;           const int slot = s * NM + m;
;           __builtin_amdgcn_sched_barrier(0);
; #pragma unroll
;           for (int pc = 0; pc < NLD; ++pc)
;             if ((pc * 2 * NM) / NLD == slot && pre) issue_piece(kt + DIST, pc);
;           __builtin_amdgcn_sched_barrier(0);
;         }
;       }
;     }
	s_waitcnt lgkmcnt(0)
	v_mfma_f32_32x32x16_bf16 v[48:63], v[186:189], v[190:193], v[48:63]
	v_mfma_f32_32x32x16_bf16 v[16:31], v[186:189], v[194:197], v[16:31]
	ds_read_b128 v[186:189], v132 offset:32768
	v_mfma_f32_32x32x16_bf16 v[32:47], v[198:201], v[190:193], v[32:47]
	ds_read_b128 v[190:193], v136
	v_mfma_f32_32x32x16_bf16 v[0:15], v[198:201], v[194:197], v[0:15]
	ds_read_b128 v[194:197], v136 offset:4096
	ds_read_b128 v[198:201], v132 offset:36864
	ds_read_b128 v[202:205], v132 offset:40960
	ds_read_b128 v[206:209], v132 offset:45056
	s_waitcnt lgkmcnt(0)
	v_mfma_f32_32x32x16_bf16 v[96:111], v[186:189], v[190:193], v[96:111]
	v_mfma_f32_32x32x16_bf16 v[64:79], v[186:189], v[194:197], v[64:79]
	v_lshl_add_u64 v[186:187], v[130:131], 0, s[0:1]
	s_mov_b32 m0, s8
	s_nop 0
	global_load_lds_dwordx4 v[186:187], off
	v_mfma_f32_32x32x16_bf16 v[112:127], v[198:201], v[190:193], v[112:127]
	v_mfma_f32_32x32x16_bf16 v[80:95], v[198:201], v[194:197], v[80:95]
	s_mov_b64 s[0:1], 0x5a000
	v_lshl_add_u64 v[186:187], v[130:131], 0, s[0:1]
	s_mov_b32 m0, s9
	s_nop 0
	global_load_lds_dwordx4 v[186:187], off
	v_mfma_f32_32x32x16_bf16 v[48:63], v[202:205], v[190:193], v[48:63]
	v_mfma_f32_32x32x16_bf16 v[16:31], v[202:205], v[194:197], v[16:31]
	s_mov_b64 s[2:3], 0x5c000
	v_lshl_add_u64 v[186:187], v[130:131], 0, s[2:3]
	s_mov_b32 m0, s10
	s_nop 0
	global_load_lds_dwordx4 v[186:187], off
	v_mfma_f32_32x32x16_bf16 v[32:47], v[206:209], v[190:193], v[32:47]
	v_mfma_f32_32x32x16_bf16 v[0:15], v[206:209], v[194:197], v[0:15]
	s_mov_b64 s[4:5], 0x5e000
	v_lshl_add_u64 v[186:187], v[130:131], 0, s[4:5]
	s_mov_b32 m0, s11
	s_nop 0
	global_load_lds_dwordx4 v[186:187], off
	ds_read_b128 v[186:189], v133 offset:32768
	ds_read_b128 v[190:193], v137
	ds_read_b128 v[194:197], v137 offset:4096
	ds_read_b128 v[198:201], v133 offset:36864
	ds_read_b128 v[202:205], v133 offset:40960
	ds_read_b128 v[206:209], v133 offset:45056
	s_waitcnt lgkmcnt(0)
	v_mfma_f32_32x32x16_bf16 v[96:111], v[186:189], v[190:193], v[96:111]
	v_mfma_f32_32x32x16_bf16 v[64:79], v[186:189], v[194:197], v[64:79]
	s_mov_b32 m0, s12
	s_nop 0
	global_load_lds_dwordx4 v[210:211], off
	v_mfma_f32_32x32x16_bf16 v[112:127], v[198:201], v[190:193], v[112:127]
	v_mfma_f32_32x32x16_bf16 v[80:95], v[198:201], v[194:197], v[80:95]
	v_lshl_add_u64 v[186:187], v[128:129], 0, s[0:1]
	s_mov_b32 m0, s13
	s_nop 0
	global_load_lds_dwordx4 v[186:187], off
	v_mfma_f32_32x32x16_bf16 v[48:63], v[202:205], v[190:193], v[48:63]
	v_mfma_f32_32x32x16_bf16 v[16:31], v[202:205], v[194:197], v[16:31]
	v_lshl_add_u64 v[186:187], v[128:129], 0, s[2:3]
	s_mov_b32 m0, s14
	s_nop 0
	global_load_lds_dwordx4 v[186:187], off
	v_mfma_f32_32x32x16_bf16 v[32:47], v[206:209], v[190:193], v[32:47]
	v_mfma_f32_32x32x16_bf16 v[0:15], v[206:209], v[194:197], v[0:15]
	v_lshl_add_u64 v[186:187], v[128:129], 0, s[4:5]
	s_mov_b32 m0, s15
	s_nop 0
	global_load_lds_dwordx4 v[186:187], off
	ds_read_b128 v[186:189], v135 offset:32768
	ds_read_b128 v[190:193], v140
	ds_read_b128 v[194:197], v140 offset:4096
	ds_read_b128 v[198:201], v135 offset:36864
	s_mov_b64 s[0:1], 0x60000
	v_lshl_add_u64 v[210:211], v[128:129], 0, s[0:1]
	s_waitcnt lgkmcnt(0)
	v_mfma_f32_32x32x16_bf16 v[96:111], v[186:189], v[190:193], v[96:111]
	v_mfma_f32_32x32x16_bf16 v[64:79], v[186:189], v[194:197], v[64:79]
	ds_read_b128 v[186:189], v135 offset:40960
	v_mfma_f32_32x32x16_bf16 v[112:127], v[198:201], v[190:193], v[112:127]
	v_mfma_f32_32x32x16_bf16 v[80:95], v[198:201], v[194:197], v[80:95]
	ds_read_b128 v[198:201], v135 offset:45056
	s_waitcnt lgkmcnt(0)
	v_mfma_f32_32x32x16_bf16 v[48:63], v[186:189], v[190:193], v[48:63]
	v_mfma_f32_32x32x16_bf16 v[16:31], v[186:189], v[194:197], v[16:31]
	ds_read_b128 v[186:189], v134 offset:32768
	v_mfma_f32_32x32x16_bf16 v[32:47], v[198:201], v[190:193], v[32:47]
	ds_read_b128 v[190:193], v139
	v_mfma_f32_32x32x16_bf16 v[0:15], v[198:201], v[194:197], v[0:15]
	ds_read_b128 v[194:197], v139 offset:4096
	ds_read_b128 v[198:201], v134 offset:36864
	s_waitcnt lgkmcnt(0)
	v_mfma_f32_32x32x16_bf16 v[96:111], v[186:189], v[190:193], v[96:111]
	v_mfma_f32_32x32x16_bf16 v[64:79], v[186:189], v[194:197], v[64:79]
	ds_read_b128 v[186:189], v134 offset:40960
	v_mfma_f32_32x32x16_bf16 v[112:127], v[198:201], v[190:193], v[112:127]
	v_mfma_f32_32x32x16_bf16 v[80:95], v[198:201], v[194:197], v[80:95]
	ds_read_b128 v[198:201], v134 offset:45056
	s_waitcnt vmcnt(0)
	s_barrier
; #define MFMA(a, b, c) __builtin_amdgcn_mfma_f32_32x32x16_bf16((a), (b), (c), 0, 0, 0)
;     ...
;   for (int kt = 0; kt < nk; ++kt) {
;     if (DIST == 2 && kt + 1 < nk) {
;       if (NLD == 6) asm volatile("s_waitcnt vmcnt(6)" ::: "memory");
;       else if (NLD == 5) asm volatile("s_waitcnt vmcnt(5)" ::: "memory");
;       else asm volatile("s_waitcnt vmcnt(8)" ::: "memory");
;     } else {
;       asm volatile("s_waitcnt vmcnt(0)" ::: "memory");
;     }
;     __builtin_amdgcn_s_barrier();
;     const bool pre = (kt + DIST < nk);
;     const char* base = smem + (kt % NSTG) * STAGE;
;     const char* pa = base + (wrow_act + r) * 128;
;     const char* pw = base + ABYTES + (wrow_w + r) * 128;
;     constexpr int NM = NI * MJ;
;     constexpr int PPS = (NLD + 1) / 2;
; #pragma unroll
;     for (int s = 0; s < 4; ++s) {
;       bf16x8 af[MJ], wf[NI];
; #pragma unroll
;       for (int j = 0; j < MJ; ++j) af[j] = *(const bf16x8*)(pa + j * 32 * 128 + xo[s]);
; #pragma unroll
;       for (int i = 0; i < NI; ++i) wf[i] = *(const bf16x8*)(pw + i * 32 * 128 + xo[s]);
; #pragma unroll
;       for (int m = 0; m < NM; ++m) {
;         const int i = m / MJ, j = m % MJ;
;         acc[i][j] = MFMA(wf[i], af[j], acc[i][j]);
;         if (s < 2 && NM >= PPS) {
;           constexpr int EVERY = (NM / PPS) > 0 ? (NM / PPS) : 1;
;           if ((m + 1) % EVERY == 0) {
;             const int pc = s * PPS + (m + 1) / EVERY - 1;
;             if ((m + 1) / EVERY <= PPS && pc < NLD) {
;               __builtin_amdgcn_sched_barrier(0);
;               if (pre) issue_piece(kt + DIST, pc);
;               __builtin_amdgcn_sched_barrier(0);
;             }
;           }
;         }
;         if (s < 2 && NM < PPS) {
;           const int slot = s * NM + m;
;           __builtin_amdgcn_sched_barrier(0);
; #pragma unroll
;           for (int pc = 0; pc < NLD; ++pc)
;             if ((pc * 2 * NM) / NLD == slot && pre) issue_piece(kt + DIST, pc);
;           __builtin_amdgcn_sched_barrier(0);
;         }
;       }
;     }
;   }
	s_waitcnt lgkmcnt(0)
	v_mfma_f32_32x32x16_bf16 v[48:63], v[186:189], v[190:193], v[48:63]
	v_mfma_f32_32x32x16_bf16 v[16:31], v[186:189], v[194:197], v[16:31]
	ds_read_b128 v[186:189], v138
	v_mfma_f32_32x32x16_bf16 v[32:47], v[198:201], v[190:193], v[32:47]
	ds_read_b128 v[190:193], v142
	v_mfma_f32_32x32x16_bf16 v[0:15], v[198:201], v[194:197], v[0:15]
	ds_read_b128 v[194:197], v142 offset:4096
	ds_read_b128 v[198:201], v138 offset:4096
	ds_read_b128 v[202:205], v138 offset:8192
	ds_read_b128 v[206:209], v138 offset:12288
	s_waitcnt lgkmcnt(0)
	v_mfma_f32_32x32x16_bf16 v[96:111], v[186:189], v[190:193], v[96:111]
	v_mfma_f32_32x32x16_bf16 v[64:79], v[186:189], v[194:197], v[64:79]
	v_lshl_add_u64 v[186:187], v[130:131], 0, s[0:1]
	v_readfirstlane_b32 s0, v184
	s_mov_b32 m0, s0
	s_nop 0
	global_load_lds_dwordx4 v[186:187], off
	v_mfma_f32_32x32x16_bf16 v[112:127], v[198:201], v[190:193], v[112:127]
	v_mfma_f32_32x32x16_bf16 v[80:95], v[198:201], v[194:197], v[80:95]
	s_mov_b64 s[6:7], 0x62000
	v_readfirstlane_b32 s1, v183
	v_lshl_add_u64 v[184:185], v[130:131], 0, s[6:7]
	s_mov_b32 m0, s1
	s_nop 0
	global_load_lds_dwordx4 v[184:185], off
	v_mfma_f32_32x32x16_bf16 v[48:63], v[202:205], v[190:193], v[48:63]
	v_mfma_f32_32x32x16_bf16 v[16:31], v[202:205], v[194:197], v[16:31]
	s_mov_b64 s[8:9], 0x64000
	v_readfirstlane_b32 s2, v182
	v_lshl_add_u64 v[184:185], v[130:131], 0, s[8:9]
	s_mov_b32 m0, s2
	s_nop 0
	global_load_lds_dwordx4 v[184:185], off
	v_mfma_f32_32x32x16_bf16 v[32:47], v[206:209], v[190:193], v[32:47]
	v_mfma_f32_32x32x16_bf16 v[0:15], v[206:209], v[194:197], v[0:15]
	s_mov_b64 s[10:11], 0x66000
	v_readfirstlane_b32 s3, v181
	v_lshl_add_u64 v[182:183], v[130:131], 0, s[10:11]
	s_mov_b32 m0, s3
	s_nop 0
	global_load_lds_dwordx4 v[182:183], off
	ds_read_b128 v[182:185], v144
	ds_read_b128 v[186:189], v151
	ds_read_b128 v[190:193], v151 offset:4096
	ds_read_b128 v[194:197], v144 offset:4096
	ds_read_b128 v[198:201], v144 offset:8192
	ds_read_b128 v[202:205], v144 offset:12288
	s_waitcnt lgkmcnt(0)
	v_mfma_f32_32x32x16_bf16 v[96:111], v[182:185], v[186:189], v[96:111]
	v_mfma_f32_32x32x16_bf16 v[64:79], v[182:185], v[190:193], v[64:79]
	v_readfirstlane_b32 s4, v162
	s_mov_b32 m0, s4
	s_nop 0
	global_load_lds_dwordx4 v[210:211], off
	v_mfma_f32_32x32x16_bf16 v[112:127], v[194:197], v[186:189], v[112:127]
	v_mfma_f32_32x32x16_bf16 v[80:95], v[194:197], v[190:193], v[80:95]
	v_readfirstlane_b32 s5, v165
	v_lshl_add_u64 v[182:183], v[128:129], 0, s[6:7]
	s_mov_b32 m0, s5
	s_nop 0
	global_load_lds_dwordx4 v[182:183], off
	v_mfma_f32_32x32x16_bf16 v[48:63], v[198:201], v[186:189], v[48:63]
	v_mfma_f32_32x32x16_bf16 v[16:31], v[198:201], v[190:193], v[16:31]
	v_readfirstlane_b32 s6, v164
	v_lshl_add_u64 v[182:183], v[128:129], 0, s[8:9]
	s_mov_b32 m0, s6
	s_nop 0
	global_load_lds_dwordx4 v[182:183], off
	v_mfma_f32_32x32x16_bf16 v[32:47], v[202:205], v[186:189], v[32:47]
	v_mfma_f32_32x32x16_bf16 v[0:15], v[202:205], v[190:193], v[0:15]
	v_readfirstlane_b32 s7, v163
	v_lshl_add_u64 v[164:165], v[128:129], 0, s[10:11]
	s_mov_b32 m0, s7
	s_nop 0
	global_load_lds_dwordx4 v[164:165], off
	ds_read_b128 v[162:165], v143
	ds_read_b128 v[182:185], v153
	ds_read_b128 v[186:189], v153 offset:4096
	ds_read_b128 v[190:193], v143 offset:4096
	s_mov_b64 s[8:9], 0x68000
	v_lshl_add_u64 v[202:203], v[128:129], 0, s[8:9]
	s_waitcnt lgkmcnt(0)
	v_mfma_f32_32x32x16_bf16 v[96:111], v[162:165], v[182:185], v[96:111]
	v_mfma_f32_32x32x16_bf16 v[64:79], v[162:165], v[186:189], v[64:79]
	ds_read_b128 v[162:165], v143 offset:8192
	v_mfma_f32_32x32x16_bf16 v[112:127], v[190:193], v[182:185], v[112:127]
	v_mfma_f32_32x32x16_bf16 v[80:95], v[190:193], v[186:189], v[80:95]
	ds_read_b128 v[190:193], v143 offset:12288
	s_waitcnt lgkmcnt(0)
	v_mfma_f32_32x32x16_bf16 v[48:63], v[162:165], v[182:185], v[48:63]
	v_mfma_f32_32x32x16_bf16 v[16:31], v[162:165], v[186:189], v[16:31]
	ds_read_b128 v[162:165], v141
	v_mfma_f32_32x32x16_bf16 v[32:47], v[190:193], v[182:185], v[32:47]
	ds_read_b128 v[182:185], v152
	v_mfma_f32_32x32x16_bf16 v[0:15], v[190:193], v[186:189], v[0:15]
	ds_read_b128 v[186:189], v152 offset:4096
	ds_read_b128 v[190:193], v141 offset:4096
	s_waitcnt lgkmcnt(0)
	v_mfma_f32_32x32x16_bf16 v[96:111], v[162:165], v[182:185], v[96:111]
	v_mfma_f32_32x32x16_bf16 v[64:79], v[162:165], v[186:189], v[64:79]
	ds_read_b128 v[162:165], v141 offset:8192
	v_mfma_f32_32x32x16_bf16 v[112:127], v[190:193], v[182:185], v[112:127]
	v_mfma_f32_32x32x16_bf16 v[80:95], v[190:193], v[186:189], v[80:95]
	ds_read_b128 v[190:193], v141 offset:12288
	s_waitcnt vmcnt(0)
	s_barrier
; #define MFMA(a, b, c) __builtin_amdgcn_mfma_f32_32x32x16_bf16((a), (b), (c), 0, 0, 0)
;     ...
;   for (int kt = 0; kt < nk; ++kt) {
;     if (DIST == 2 && kt + 1 < nk) {
;       if (NLD == 6) asm volatile("s_waitcnt vmcnt(6)" ::: "memory");
;       else if (NLD == 5) asm volatile("s_waitcnt vmcnt(5)" ::: "memory");
;       else asm volatile("s_waitcnt vmcnt(8)" ::: "memory");
;     } else {
;       asm volatile("s_waitcnt vmcnt(0)" ::: "memory");
;     }
;     __builtin_amdgcn_s_barrier();
;     const bool pre = (kt + DIST < nk);
;     const char* base = smem + (kt % NSTG) * STAGE;
;     const char* pa = base + (wrow_act + r) * 128;
;     const char* pw = base + ABYTES + (wrow_w + r) * 128;
;     constexpr int NM = NI * MJ;
;     constexpr int PPS = (NLD + 1) / 2;
; #pragma unroll
;     for (int s = 0; s < 4; ++s) {
;       bf16x8 af[MJ], wf[NI];
; #pragma unroll
;       for (int j = 0; j < MJ; ++j) af[j] = *(const bf16x8*)(pa + j * 32 * 128 + xo[s]);
; #pragma unroll
;       for (int i = 0; i < NI; ++i) wf[i] = *(const bf16x8*)(pw + i * 32 * 128 + xo[s]);
; #pragma unroll
;       for (int m = 0; m < NM; ++m) {
;         const int i = m / MJ, j = m % MJ;
;         acc[i][j] = MFMA(wf[i], af[j], acc[i][j]);
;         if (s < 2 && NM >= PPS) {
;           constexpr int EVERY = (NM / PPS) > 0 ? (NM / PPS) : 1;
;           if ((m + 1) % EVERY == 0) {
;             const int pc = s * PPS + (m + 1) / EVERY - 1;
;             if ((m + 1) / EVERY <= PPS && pc < NLD) {
;               __builtin_amdgcn_sched_barrier(0);
;               if (pre) issue_piece(kt + DIST, pc);
;               __builtin_amdgcn_sched_barrier(0);
;             }
;           }
;         }
;         if (s < 2 && NM < PPS) {
;           const int slot = s * NM + m;
;           __builtin_amdgcn_sched_barrier(0);
; #pragma unroll
;           for (int pc = 0; pc < NLD; ++pc)
;             if ((pc * 2 * NM) / NLD == slot && pre) issue_piece(kt + DIST, pc);
;           __builtin_amdgcn_sched_barrier(0);
;         }
;       }
;     }
;   }
	s_waitcnt lgkmcnt(0)
	v_mfma_f32_32x32x16_bf16 v[48:63], v[162:165], v[182:185], v[48:63]
	v_mfma_f32_32x32x16_bf16 v[16:31], v[162:165], v[186:189], v[16:31]
	ds_read_b128 v[162:165], v132 offset:32768
	v_mfma_f32_32x32x16_bf16 v[32:47], v[190:193], v[182:185], v[32:47]
	ds_read_b128 v[182:185], v136
	v_mfma_f32_32x32x16_bf16 v[0:15], v[190:193], v[186:189], v[0:15]
	ds_read_b128 v[186:189], v136 offset:4096
	ds_read_b128 v[190:193], v132 offset:36864
	ds_read_b128 v[194:197], v132 offset:40960
	ds_read_b128 v[198:201], v132 offset:45056
	s_waitcnt lgkmcnt(0)
	v_mfma_f32_32x32x16_bf16 v[96:111], v[162:165], v[182:185], v[96:111]
	v_mfma_f32_32x32x16_bf16 v[64:79], v[162:165], v[186:189], v[64:79]
	v_lshl_add_u64 v[162:163], v[130:131], 0, s[8:9]
	v_readfirstlane_b32 s8, v155
	s_mov_b32 m0, s8
	s_nop 0
	global_load_lds_dwordx4 v[162:163], off
	v_mfma_f32_32x32x16_bf16 v[112:127], v[190:193], v[182:185], v[112:127]
	v_mfma_f32_32x32x16_bf16 v[80:95], v[190:193], v[186:189], v[80:95]
	s_mov_b64 s[14:15], 0x6a000
	v_readfirstlane_b32 s9, v158
	v_lshl_add_u64 v[162:163], v[130:131], 0, s[14:15]
	s_mov_b32 m0, s9
	s_nop 0
	global_load_lds_dwordx4 v[162:163], off
	v_mfma_f32_32x32x16_bf16 v[48:63], v[194:197], v[182:185], v[48:63]
	v_mfma_f32_32x32x16_bf16 v[16:31], v[194:197], v[186:189], v[16:31]
	s_mov_b64 s[16:17], 0x6c000
	v_readfirstlane_b32 s10, v157
	v_lshl_add_u64 v[162:163], v[130:131], 0, s[16:17]
	s_mov_b32 m0, s10
	s_nop 0
	global_load_lds_dwordx4 v[162:163], off
	v_mfma_f32_32x32x16_bf16 v[32:47], v[198:201], v[182:185], v[32:47]
	v_mfma_f32_32x32x16_bf16 v[0:15], v[198:201], v[186:189], v[0:15]
	s_mov_b64 s[18:19], 0x6e000
	v_readfirstlane_b32 s11, v156
	v_lshl_add_u64 v[162:163], v[130:131], 0, s[18:19]
	s_mov_b32 m0, s11
	s_nop 0
	global_load_lds_dwordx4 v[162:163], off
	ds_read_b128 v[162:165], v133 offset:32768
	ds_read_b128 v[182:185], v137
	ds_read_b128 v[186:189], v137 offset:4096
	ds_read_b128 v[190:193], v133 offset:36864
	ds_read_b128 v[194:197], v133 offset:40960
	ds_read_b128 v[198:201], v133 offset:45056
	s_waitcnt lgkmcnt(0)
	v_mfma_f32_32x32x16_bf16 v[96:111], v[162:165], v[182:185], v[96:111]
	v_mfma_f32_32x32x16_bf16 v[64:79], v[162:165], v[186:189], v[64:79]
	v_readfirstlane_b32 s12, v154
	s_mov_b32 m0, s12
	s_nop 0
	global_load_lds_dwordx4 v[202:203], off
	v_mfma_f32_32x32x16_bf16 v[112:127], v[190:193], v[182:185], v[112:127]
	v_mfma_f32_32x32x16_bf16 v[80:95], v[190:193], v[186:189], v[80:95]
	v_readfirstlane_b32 s13, v159
	v_lshl_add_u64 v[154:155], v[128:129], 0, s[14:15]
	s_mov_b32 m0, s13
	s_nop 0
	global_load_lds_dwordx4 v[154:155], off
	v_mfma_f32_32x32x16_bf16 v[48:63], v[194:197], v[182:185], v[48:63]
	v_mfma_f32_32x32x16_bf16 v[16:31], v[194:197], v[186:189], v[16:31]
	v_readfirstlane_b32 s14, v160
	v_lshl_add_u64 v[154:155], v[128:129], 0, s[16:17]
	s_mov_b32 m0, s14
	s_nop 0
	global_load_lds_dwordx4 v[154:155], off
	v_mfma_f32_32x32x16_bf16 v[32:47], v[198:201], v[182:185], v[32:47]
	v_mfma_f32_32x32x16_bf16 v[0:15], v[198:201], v[186:189], v[0:15]
	v_readfirstlane_b32 s15, v161
	v_lshl_add_u64 v[154:155], v[128:129], 0, s[18:19]
	s_mov_b32 m0, s15
	s_nop 0
	global_load_lds_dwordx4 v[154:155], off
	ds_read_b128 v[154:157], v135 offset:32768
	ds_read_b128 v[158:161], v140
	ds_read_b128 v[162:165], v140 offset:4096
	ds_read_b128 v[182:185], v135 offset:36864
	s_mov_b64 s[16:17], 0x70000
	v_lshl_add_u64 v[194:195], v[128:129], 0, s[16:17]
	s_waitcnt lgkmcnt(0)
	v_mfma_f32_32x32x16_bf16 v[96:111], v[154:157], v[158:161], v[96:111]
	v_mfma_f32_32x32x16_bf16 v[64:79], v[154:157], v[162:165], v[64:79]
	ds_read_b128 v[154:157], v135 offset:40960
	v_mfma_f32_32x32x16_bf16 v[112:127], v[182:185], v[158:161], v[112:127]
	v_mfma_f32_32x32x16_bf16 v[80:95], v[182:185], v[162:165], v[80:95]
	ds_read_b128 v[182:185], v135 offset:45056
	s_waitcnt lgkmcnt(0)
	v_mfma_f32_32x32x16_bf16 v[48:63], v[154:157], v[158:161], v[48:63]
	v_mfma_f32_32x32x16_bf16 v[16:31], v[154:157], v[162:165], v[16:31]
	ds_read_b128 v[154:157], v134 offset:32768
	v_mfma_f32_32x32x16_bf16 v[32:47], v[182:185], v[158:161], v[32:47]
	ds_read_b128 v[158:161], v139
	v_mfma_f32_32x32x16_bf16 v[0:15], v[182:185], v[162:165], v[0:15]
	ds_read_b128 v[162:165], v139 offset:4096
	ds_read_b128 v[182:185], v134 offset:36864
	s_waitcnt lgkmcnt(0)
	v_mfma_f32_32x32x16_bf16 v[96:111], v[154:157], v[158:161], v[96:111]
	v_mfma_f32_32x32x16_bf16 v[64:79], v[154:157], v[162:165], v[64:79]
	ds_read_b128 v[154:157], v134 offset:40960
	v_mfma_f32_32x32x16_bf16 v[112:127], v[182:185], v[158:161], v[112:127]
	v_mfma_f32_32x32x16_bf16 v[80:95], v[182:185], v[162:165], v[80:95]
	ds_read_b128 v[182:185], v134 offset:45056
	s_waitcnt vmcnt(0)
	s_barrier
; #define MFMA(a, b, c) __builtin_amdgcn_mfma_f32_32x32x16_bf16((a), (b), (c), 0, 0, 0)
;     ...
;   for (int kt = 0; kt < nk; ++kt) {
;     if (DIST == 2 && kt + 1 < nk) {
;       if (NLD == 6) asm volatile("s_waitcnt vmcnt(6)" ::: "memory");
;       else if (NLD == 5) asm volatile("s_waitcnt vmcnt(5)" ::: "memory");
;       else asm volatile("s_waitcnt vmcnt(8)" ::: "memory");
;     } else {
;       asm volatile("s_waitcnt vmcnt(0)" ::: "memory");
;     }
;     __builtin_amdgcn_s_barrier();
;     const bool pre = (kt + DIST < nk);
;     const char* base = smem + (kt % NSTG) * STAGE;
;     const char* pa = base + (wrow_act + r) * 128;
;     const char* pw = base + ABYTES + (wrow_w + r) * 128;
;     constexpr int NM = NI * MJ;
;     constexpr int PPS = (NLD + 1) / 2;
; #pragma unroll
;     for (int s = 0; s < 4; ++s) {
;       bf16x8 af[MJ], wf[NI];
; #pragma unroll
;       for (int j = 0; j < MJ; ++j) af[j] = *(const bf16x8*)(pa + j * 32 * 128 + xo[s]);
; #pragma unroll
;       for (int i = 0; i < NI; ++i) wf[i] = *(const bf16x8*)(pw + i * 32 * 128 + xo[s]);
; #pragma unroll
;       for (int m = 0; m < NM; ++m) {
;         const int i = m / MJ, j = m % MJ;
;         acc[i][j] = MFMA(wf[i], af[j], acc[i][j]);
;         if (s < 2 && NM >= PPS) {
;           constexpr int EVERY = (NM / PPS) > 0 ? (NM / PPS) : 1;
;           if ((m + 1) % EVERY == 0) {
;             const int pc = s * PPS + (m + 1) / EVERY - 1;
;             if ((m + 1) / EVERY <= PPS && pc < NLD) {
;               __builtin_amdgcn_sched_barrier(0);
;               if (pre) issue_piece(kt + DIST, pc);
;               __builtin_amdgcn_sched_barrier(0);
;             }
;           }
;         }
;         if (s < 2 && NM < PPS) {
;           const int slot = s * NM + m;
;           __builtin_amdgcn_sched_barrier(0);
; #pragma unroll
;           for (int pc = 0; pc < NLD; ++pc)
;             if ((pc * 2 * NM) / NLD == slot && pre) issue_piece(kt + DIST, pc);
;           __builtin_amdgcn_sched_barrier(0);
;         }
;       }
;     }
;   }
	s_waitcnt lgkmcnt(0)
	v_mfma_f32_32x32x16_bf16 v[48:63], v[154:157], v[158:161], v[48:63]
	v_mfma_f32_32x32x16_bf16 v[16:31], v[154:157], v[162:165], v[16:31]
	ds_read_b128 v[154:157], v138
	v_mfma_f32_32x32x16_bf16 v[32:47], v[182:185], v[158:161], v[32:47]
	ds_read_b128 v[158:161], v142
	v_mfma_f32_32x32x16_bf16 v[0:15], v[182:185], v[162:165], v[0:15]
	ds_read_b128 v[162:165], v142 offset:4096
	ds_read_b128 v[182:185], v138 offset:4096
	ds_read_b128 v[186:189], v138 offset:8192
	ds_read_b128 v[190:193], v138 offset:12288
	s_waitcnt lgkmcnt(0)
	v_mfma_f32_32x32x16_bf16 v[96:111], v[154:157], v[158:161], v[96:111]
	v_mfma_f32_32x32x16_bf16 v[64:79], v[154:157], v[162:165], v[64:79]
	v_lshl_add_u64 v[154:155], v[130:131], 0, s[16:17]
	s_mov_b32 m0, s0
	s_nop 0
	global_load_lds_dwordx4 v[154:155], off
	v_mfma_f32_32x32x16_bf16 v[112:127], v[182:185], v[158:161], v[112:127]
	v_mfma_f32_32x32x16_bf16 v[80:95], v[182:185], v[162:165], v[80:95]
	s_mov_b64 s[16:17], 0x72000
	v_lshl_add_u64 v[154:155], v[130:131], 0, s[16:17]
	s_mov_b32 m0, s1
	s_nop 0
	global_load_lds_dwordx4 v[154:155], off
	v_mfma_f32_32x32x16_bf16 v[48:63], v[186:189], v[158:161], v[48:63]
	v_mfma_f32_32x32x16_bf16 v[16:31], v[186:189], v[162:165], v[16:31]
	s_mov_b64 s[0:1], 0x74000
	v_lshl_add_u64 v[154:155], v[130:131], 0, s[0:1]
	s_mov_b32 m0, s2
	s_nop 0
	global_load_lds_dwordx4 v[154:155], off
	v_mfma_f32_32x32x16_bf16 v[32:47], v[190:193], v[158:161], v[32:47]
	v_mfma_f32_32x32x16_bf16 v[0:15], v[190:193], v[162:165], v[0:15]
	s_mov_b64 s[18:19], 0x76000
	v_lshl_add_u64 v[154:155], v[130:131], 0, s[18:19]
	s_mov_b32 m0, s3
	s_nop 0
	global_load_lds_dwordx4 v[154:155], off
	ds_read_b128 v[154:157], v144
	ds_read_b128 v[158:161], v151
	ds_read_b128 v[162:165], v151 offset:4096
	ds_read_b128 v[182:185], v144 offset:4096
	ds_read_b128 v[186:189], v144 offset:8192
	ds_read_b128 v[190:193], v144 offset:12288
	s_waitcnt lgkmcnt(0)
	v_mfma_f32_32x32x16_bf16 v[96:111], v[154:157], v[158:161], v[96:111]
	v_mfma_f32_32x32x16_bf16 v[64:79], v[154:157], v[162:165], v[64:79]
	s_mov_b32 m0, s4
	s_nop 0
	global_load_lds_dwordx4 v[194:195], off
	v_mfma_f32_32x32x16_bf16 v[112:127], v[182:185], v[158:161], v[112:127]
	v_mfma_f32_32x32x16_bf16 v[80:95], v[182:185], v[162:165], v[80:95]
	v_lshl_add_u64 v[154:155], v[128:129], 0, s[16:17]
	s_mov_b32 m0, s5
	s_nop 0
	global_load_lds_dwordx4 v[154:155], off
	v_mfma_f32_32x32x16_bf16 v[48:63], v[186:189], v[158:161], v[48:63]
	v_mfma_f32_32x32x16_bf16 v[16:31], v[186:189], v[162:165], v[16:31]
	v_lshl_add_u64 v[154:155], v[128:129], 0, s[0:1]
	s_mov_b32 m0, s6
	s_nop 0
	global_load_lds_dwordx4 v[154:155], off
	v_mfma_f32_32x32x16_bf16 v[32:47], v[190:193], v[158:161], v[32:47]
	v_mfma_f32_32x32x16_bf16 v[0:15], v[190:193], v[162:165], v[0:15]
	v_lshl_add_u64 v[154:155], v[128:129], 0, s[18:19]
	s_mov_b32 m0, s7
	s_nop 0
	global_load_lds_dwordx4 v[154:155], off
	ds_read_b128 v[154:157], v143
	ds_read_b128 v[158:161], v153
	ds_read_b128 v[162:165], v153 offset:4096
	ds_read_b128 v[182:185], v143 offset:4096
	s_mov_b64 s[0:1], 0x78000
	v_lshl_add_u64 v[194:195], v[128:129], 0, s[0:1]
	s_waitcnt lgkmcnt(0)
	v_mfma_f32_32x32x16_bf16 v[96:111], v[154:157], v[158:161], v[96:111]
	v_mfma_f32_32x32x16_bf16 v[64:79], v[154:157], v[162:165], v[64:79]
	ds_read_b128 v[154:157], v143 offset:8192
	v_mfma_f32_32x32x16_bf16 v[112:127], v[182:185], v[158:161], v[112:127]
	v_mfma_f32_32x32x16_bf16 v[80:95], v[182:185], v[162:165], v[80:95]
	ds_read_b128 v[182:185], v143 offset:12288
	s_waitcnt lgkmcnt(0)
	v_mfma_f32_32x32x16_bf16 v[48:63], v[154:157], v[158:161], v[48:63]
	v_mfma_f32_32x32x16_bf16 v[16:31], v[154:157], v[162:165], v[16:31]
	ds_read_b128 v[154:157], v141
	v_mfma_f32_32x32x16_bf16 v[32:47], v[182:185], v[158:161], v[32:47]
	ds_read_b128 v[158:161], v152
	v_mfma_f32_32x32x16_bf16 v[0:15], v[182:185], v[162:165], v[0:15]
	ds_read_b128 v[162:165], v152 offset:4096
	ds_read_b128 v[182:185], v141 offset:4096
	s_waitcnt lgkmcnt(0)
	v_mfma_f32_32x32x16_bf16 v[96:111], v[154:157], v[158:161], v[96:111]
	v_mfma_f32_32x32x16_bf16 v[64:79], v[154:157], v[162:165], v[64:79]
	ds_read_b128 v[154:157], v141 offset:8192
	v_mfma_f32_32x32x16_bf16 v[112:127], v[182:185], v[158:161], v[112:127]
	v_mfma_f32_32x32x16_bf16 v[80:95], v[182:185], v[162:165], v[80:95]
	ds_read_b128 v[182:185], v141 offset:12288
	s_waitcnt vmcnt(0)
	s_barrier
; #define MFMA(a, b, c) __builtin_amdgcn_mfma_f32_32x32x16_bf16((a), (b), (c), 0, 0, 0)
;     ...
;   for (int kt = 0; kt < nk; ++kt) {
;     if (DIST == 2 && kt + 1 < nk) {
;       if (NLD == 6) asm volatile("s_waitcnt vmcnt(6)" ::: "memory");
;       else if (NLD == 5) asm volatile("s_waitcnt vmcnt(5)" ::: "memory");
;       else asm volatile("s_waitcnt vmcnt(8)" ::: "memory");
;     } else {
;       asm volatile("s_waitcnt vmcnt(0)" ::: "memory");
;     }
;     __builtin_amdgcn_s_barrier();
;     const bool pre = (kt + DIST < nk);
;     const char* base = smem + (kt % NSTG) * STAGE;
;     const char* pa = base + (wrow_act + r) * 128;
;     const char* pw = base + ABYTES + (wrow_w + r) * 128;
;     constexpr int NM = NI * MJ;
;     constexpr int PPS = (NLD + 1) / 2;
; #pragma unroll
;     for (int s = 0; s < 4; ++s) {
;       bf16x8 af[MJ], wf[NI];
; #pragma unroll
;       for (int j = 0; j < MJ; ++j) af[j] = *(const bf16x8*)(pa + j * 32 * 128 + xo[s]);
; #pragma unroll
;       for (int i = 0; i < NI; ++i) wf[i] = *(const bf16x8*)(pw + i * 32 * 128 + xo[s]);
; #pragma unroll
;       for (int m = 0; m < NM; ++m) {
;         const int i = m / MJ, j = m % MJ;
;         acc[i][j] = MFMA(wf[i], af[j], acc[i][j]);
;         if (s < 2 && NM >= PPS) {
;           constexpr int EVERY = (NM / PPS) > 0 ? (NM / PPS) : 1;
;           if ((m + 1) % EVERY == 0) {
;             const int pc = s * PPS + (m + 1) / EVERY - 1;
;             if ((m + 1) / EVERY <= PPS && pc < NLD) {
;               __builtin_amdgcn_sched_barrier(0);
;               if (pre) issue_piece(kt + DIST, pc);
;               __builtin_amdgcn_sched_barrier(0);
;             }
;           }
;         }
;         if (s < 2 && NM < PPS) {
;           const int slot = s * NM + m;
;           __builtin_amdgcn_sched_barrier(0);
; #pragma unroll
;           for (int pc = 0; pc < NLD; ++pc)
;             if ((pc * 2 * NM) / NLD == slot && pre) issue_piece(kt + DIST, pc);
;           __builtin_amdgcn_sched_barrier(0);
;         }
;       }
;     }
;   }
	s_waitcnt lgkmcnt(0)
	v_mfma_f32_32x32x16_bf16 v[48:63], v[154:157], v[158:161], v[48:63]
	v_mfma_f32_32x32x16_bf16 v[16:31], v[154:157], v[162:165], v[16:31]
	ds_read_b128 v[154:157], v132 offset:32768
	v_mfma_f32_32x32x16_bf16 v[32:47], v[182:185], v[158:161], v[32:47]
	ds_read_b128 v[158:161], v136
	v_mfma_f32_32x32x16_bf16 v[0:15], v[182:185], v[162:165], v[0:15]
	ds_read_b128 v[162:165], v136 offset:4096
	ds_read_b128 v[182:185], v132 offset:36864
	ds_read_b128 v[186:189], v132 offset:40960
	ds_read_b128 v[190:193], v132 offset:45056
	s_waitcnt lgkmcnt(0)
	v_mfma_f32_32x32x16_bf16 v[96:111], v[154:157], v[158:161], v[96:111]
	v_mfma_f32_32x32x16_bf16 v[64:79], v[154:157], v[162:165], v[64:79]
	v_lshl_add_u64 v[154:155], v[130:131], 0, s[0:1]
	s_mov_b32 m0, s8
	s_nop 0
	global_load_lds_dwordx4 v[154:155], off
	v_mfma_f32_32x32x16_bf16 v[112:127], v[182:185], v[158:161], v[112:127]
	v_mfma_f32_32x32x16_bf16 v[80:95], v[182:185], v[162:165], v[80:95]
	s_mov_b64 s[0:1], 0x7a000
	v_lshl_add_u64 v[154:155], v[130:131], 0, s[0:1]
	s_mov_b32 m0, s9
	s_nop 0
	global_load_lds_dwordx4 v[154:155], off
	v_mfma_f32_32x32x16_bf16 v[48:63], v[186:189], v[158:161], v[48:63]
	v_mfma_f32_32x32x16_bf16 v[16:31], v[186:189], v[162:165], v[16:31]
	s_mov_b64 s[2:3], 0x7c000
	v_lshl_add_u64 v[154:155], v[130:131], 0, s[2:3]
	s_mov_b32 m0, s10
	s_nop 0
	global_load_lds_dwordx4 v[154:155], off
	ds_read_b128 v[154:157], v133 offset:32768
	v_mfma_f32_32x32x16_bf16 v[32:47], v[190:193], v[158:161], v[32:47]
	ds_read_b128 v[158:161], v137
	v_mfma_f32_32x32x16_bf16 v[0:15], v[190:193], v[162:165], v[0:15]
	s_mov_b64 s[4:5], 0x7e000
	v_lshl_add_u64 v[130:131], v[130:131], 0, s[4:5]
	s_mov_b32 m0, s11
	s_nop 0
	global_load_lds_dwordx4 v[130:131], off
	ds_read_b128 v[162:165], v137 offset:4096
	ds_read_b128 v[182:185], v133 offset:36864
	ds_read_b128 v[186:189], v133 offset:40960
	ds_read_b128 v[130:133], v133 offset:45056
	s_waitcnt lgkmcnt(0)
	v_mfma_f32_32x32x16_bf16 v[96:111], v[154:157], v[158:161], v[96:111]
	v_mfma_f32_32x32x16_bf16 v[64:79], v[154:157], v[162:165], v[64:79]
	s_mov_b32 m0, s12
	s_nop 0
	global_load_lds_dwordx4 v[194:195], off
	v_mfma_f32_32x32x16_bf16 v[112:127], v[182:185], v[158:161], v[112:127]
	v_mfma_f32_32x32x16_bf16 v[80:95], v[182:185], v[162:165], v[80:95]
	v_lshl_add_u64 v[136:137], v[128:129], 0, s[0:1]
	s_mov_b32 m0, s13
	s_nop 0
	global_load_lds_dwordx4 v[136:137], off
	v_mfma_f32_32x32x16_bf16 v[48:63], v[186:189], v[158:161], v[48:63]
	v_mfma_f32_32x32x16_bf16 v[16:31], v[186:189], v[162:165], v[16:31]
	v_lshl_add_u64 v[136:137], v[128:129], 0, s[2:3]
	s_mov_b32 m0, s14
	s_nop 0
	global_load_lds_dwordx4 v[136:137], off
	v_mfma_f32_32x32x16_bf16 v[32:47], v[130:133], v[158:161], v[32:47]
	v_mfma_f32_32x32x16_bf16 v[0:15], v[130:133], v[162:165], v[0:15]
	v_lshl_add_u64 v[128:129], v[128:129], 0, s[4:5]
	s_mov_b32 m0, s15
	s_nop 0
	global_load_lds_dwordx4 v[128:129], off
	ds_read_b128 v[128:131], v135 offset:32768
	ds_read_b128 v[154:157], v140
	ds_read_b128 v[158:161], v140 offset:4096
	ds_read_b128 v[162:165], v135 offset:36864
	s_waitcnt lgkmcnt(0)
	v_mfma_f32_32x32x16_bf16 v[96:111], v[128:131], v[154:157], v[96:111]
	v_mfma_f32_32x32x16_bf16 v[64:79], v[128:131], v[158:161], v[64:79]
	ds_read_b128 v[128:131], v135 offset:40960
	v_mfma_f32_32x32x16_bf16 v[112:127], v[162:165], v[154:157], v[112:127]
	v_mfma_f32_32x32x16_bf16 v[80:95], v[162:165], v[158:161], v[80:95]
	ds_read_b128 v[162:165], v135 offset:45056
	s_waitcnt lgkmcnt(0)
	v_mfma_f32_32x32x16_bf16 v[48:63], v[128:131], v[154:157], v[48:63]
	v_mfma_f32_32x32x16_bf16 v[16:31], v[128:131], v[158:161], v[16:31]
	ds_read_b128 v[128:131], v134 offset:32768
	v_mfma_f32_32x32x16_bf16 v[32:47], v[162:165], v[154:157], v[32:47]
	ds_read_b128 v[154:157], v139
	v_mfma_f32_32x32x16_bf16 v[0:15], v[162:165], v[158:161], v[0:15]
	ds_read_b128 v[158:161], v139 offset:4096
	ds_read_b128 v[162:165], v134 offset:36864
	s_waitcnt lgkmcnt(0)
	v_mfma_f32_32x32x16_bf16 v[96:111], v[128:131], v[154:157], v[96:111]
	v_mfma_f32_32x32x16_bf16 v[64:79], v[128:131], v[158:161], v[64:79]
	ds_read_b128 v[128:131], v134 offset:40960
	ds_read_b128 v[132:135], v134 offset:45056
	s_waitcnt vmcnt(0)
	s_barrier
;     ...
;   for (int kt = 0; kt < nk; ++kt) {
;     if (DIST == 2 && kt + 1 < nk) {
;       if (NLD == 6) asm volatile("s_waitcnt vmcnt(6)" ::: "memory");
;       else if (NLD == 5) asm volatile("s_waitcnt vmcnt(5)" ::: "memory");
;       else asm volatile("s_waitcnt vmcnt(8)" ::: "memory");
;     } else {
;       asm volatile("s_waitcnt vmcnt(0)" ::: "memory");
;     }
;     __builtin_amdgcn_s_barrier();
;     const bool pre = (kt + DIST < nk);
;     const char* base = smem + (kt % NSTG) * STAGE;
;     const char* pa = base + (wrow_act + r) * 128;
;     const char* pw = base + ABYTES + (wrow_w + r) * 128;
;     constexpr int NM = NI * MJ;
;     constexpr int PPS = (NLD + 1) / 2;
; #pragma unroll
;     for (int s = 0; s < 4; ++s) {
;       bf16x8 af[MJ], wf[NI];
; #pragma unroll
;       for (int j = 0; j < MJ; ++j) af[j] = *(const bf16x8*)(pa + j * 32 * 128 + xo[s]);
; #pragma unroll
;       for (int i = 0; i < NI; ++i) wf[i] = *(const bf16x8*)(pw + i * 32 * 128 + xo[s]);
; #pragma unroll
;       for (int m = 0; m < NM; ++m) {
;         const int i = m / MJ, j = m % MJ;
;         acc[i][j] = MFMA(wf[i], af[j], acc[i][j]);
;         if (s < 2 && NM >= PPS) {
;           constexpr int EVERY = (NM / PPS) > 0 ? (NM / PPS) : 1;
;           if ((m + 1) % EVERY == 0) {
;             const int pc = s * PPS + (m + 1) / EVERY - 1;
;             if ((m + 1) / EVERY <= PPS && pc < NLD) {
;               __builtin_amdgcn_sched_barrier(0);
;               if (pre) issue_piece(kt + DIST, pc);
;               __builtin_amdgcn_sched_barrier(0);
;             }
;           }
;         }
;         if (s < 2 && NM < PPS) {
;           const int slot = s * NM + m;
;           __builtin_amdgcn_sched_barrier(0);
; #pragma unroll
;           for (int pc = 0; pc < NLD; ++pc)
;             if ((pc * 2 * NM) / NLD == slot && pre) issue_piece(kt + DIST, pc);
;           __builtin_amdgcn_sched_barrier(0);
;         }
;       }
;     }
;   }
;   __builtin_amdgcn_s_barrier();
; DEV void inproj_epilogue(f32x16 (&acc)[2][2], int fb, int m0w, const Params& p, int l) {
;     ...
;   if (fb == 34) {
;     float* dst = (float*)(ws + OFF_KROPE);
; #pragma unroll
;     for (int j = 0; j < 2; ++j) {
;       const int m = m0w + 32 * j + r;
; #pragma unroll
;       for (int g4 = 0; g4 < 4; ++g4)
;         *(float4*)(dst + (size_t)m * 32 + 8 * g4 + 4 * h) =
	v_mfma_f32_32x32x16_bf16 v[112:127], v[162:165], v[154:157], v[112:127]
	v_mfma_f32_32x32x16_bf16 v[80:95], v[162:165], v[158:161], v[80:95]
	s_waitcnt lgkmcnt(0)
	v_mfma_f32_32x32x16_bf16 v[48:63], v[128:131], v[154:157], v[48:63]
	v_mfma_f32_32x32x16_bf16 v[16:31], v[128:131], v[158:161], v[16:31]
	ds_read_b128 v[128:131], v138
	v_mfma_f32_32x32x16_bf16 v[32:47], v[132:135], v[154:157], v[32:47]
	v_mfma_f32_32x32x16_bf16 v[0:15], v[132:135], v[158:161], v[0:15]
	ds_read_b128 v[132:135], v142
	ds_read_b128 v[154:157], v142 offset:4096
	ds_read_b128 v[158:161], v138 offset:4096
	ds_read_b128 v[162:165], v138 offset:8192
	ds_read_b128 v[136:139], v138 offset:12288
	s_waitcnt lgkmcnt(0)
	v_mfma_f32_32x32x16_bf16 v[96:111], v[128:131], v[132:135], v[96:111]
	v_mfma_f32_32x32x16_bf16 v[64:79], v[128:131], v[154:157], v[64:79]
	ds_read_b128 v[128:131], v144
	v_mfma_f32_32x32x16_bf16 v[112:127], v[158:161], v[132:135], v[112:127]
	v_mfma_f32_32x32x16_bf16 v[80:95], v[158:161], v[154:157], v[80:95]
	v_mfma_f32_32x32x16_bf16 v[48:63], v[162:165], v[132:135], v[48:63]
	v_mfma_f32_32x32x16_bf16 v[16:31], v[162:165], v[154:157], v[16:31]
	v_mfma_f32_32x32x16_bf16 v[32:47], v[136:139], v[132:135], v[32:47]
	ds_read_b128 v[132:135], v151
	v_mfma_f32_32x32x16_bf16 v[0:15], v[136:139], v[154:157], v[0:15]
	ds_read_b128 v[136:139], v151 offset:4096
	ds_read_b128 v[154:157], v144 offset:4096
	ds_read_b128 v[158:161], v144 offset:8192
	ds_read_b128 v[162:165], v144 offset:12288
	s_waitcnt lgkmcnt(0)
	v_mfma_f32_32x32x16_bf16 v[96:111], v[128:131], v[132:135], v[96:111]
	v_mfma_f32_32x32x16_bf16 v[64:79], v[128:131], v[136:139], v[64:79]
	ds_read_b128 v[128:131], v143
	v_mfma_f32_32x32x16_bf16 v[112:127], v[154:157], v[132:135], v[112:127]
	v_mfma_f32_32x32x16_bf16 v[80:95], v[154:157], v[136:139], v[80:95]
	v_mfma_f32_32x32x16_bf16 v[48:63], v[158:161], v[132:135], v[48:63]
	v_mfma_f32_32x32x16_bf16 v[16:31], v[158:161], v[136:139], v[16:31]
	v_mfma_f32_32x32x16_bf16 v[32:47], v[162:165], v[132:135], v[32:47]
	ds_read_b128 v[132:135], v153
	v_mfma_f32_32x32x16_bf16 v[0:15], v[162:165], v[136:139], v[0:15]
	ds_read_b128 v[136:139], v153 offset:4096
	s_lshl_b32 s27, s50, 2
	v_readlane_b32 s0, v242, 1
	v_readlane_b32 s2, v242, 3
	s_waitcnt lgkmcnt(0)
	v_mfma_f32_32x32x16_bf16 v[96:111], v[128:131], v[132:135], v[96:111]
	v_readlane_b32 s3, v242, 4
	v_readlane_b32 s6, v242, 7
	v_readlane_b32 s7, v242, 8
	v_readlane_b32 s1, v242, 2
	s_mov_b64 s[2:3], s[6:7]
	v_lshl_add_u32 v151, s52, 8, v146
	v_readlane_b32 s4, v242, 5
	v_mfma_f32_32x32x16_bf16 v[64:79], v[128:131], v[136:139], v[64:79]
	ds_read_b128 v[128:131], v143 offset:4096
	v_readlane_b32 s5, v242, 6
	s_waitcnt lgkmcnt(0)
	v_mfma_f32_32x32x16_bf16 v[112:127], v[128:131], v[132:135], v[112:127]
	v_mfma_f32_32x32x16_bf16 v[80:95], v[128:131], v[136:139], v[80:95]
	ds_read_b128 v[128:131], v143 offset:8192
	s_waitcnt lgkmcnt(0)
	v_mfma_f32_32x32x16_bf16 v[48:63], v[128:131], v[132:135], v[48:63]
	v_mfma_f32_32x32x16_bf16 v[16:31], v[128:131], v[136:139], v[16:31]
	ds_read_b128 v[128:131], v143 offset:12288
	s_waitcnt lgkmcnt(0)
	v_mfma_f32_32x32x16_bf16 v[32:47], v[128:131], v[132:135], v[32:47]
	v_mfma_f32_32x32x16_bf16 v[0:15], v[128:131], v[136:139], v[0:15]
	ds_read_b128 v[128:131], v141
	ds_read_b128 v[132:135], v152
	ds_read_b128 v[154:157], v152 offset:4096
	v_or_b32_e32 v152, s27, v148
	v_cmp_lt_i32_e64 s[38:39], 15, v152
	s_waitcnt lgkmcnt(0)
	v_mfma_f32_32x32x16_bf16 v[96:111], v[128:131], v[132:135], v[96:111]
	v_mfma_f32_32x32x16_bf16 v[64:79], v[128:131], v[154:157], v[64:79]
	ds_read_b128 v[128:131], v141 offset:4096
	s_waitcnt lgkmcnt(0)
	v_mfma_f32_32x32x16_bf16 v[112:127], v[128:131], v[132:135], v[112:127]
	v_mfma_f32_32x32x16_bf16 v[80:95], v[128:131], v[154:157], v[80:95]
	ds_read_b128 v[128:131], v141 offset:8192
	ds_read_b128 v[138:141], v141 offset:12288
	s_barrier
	s_waitcnt lgkmcnt(0)
	v_mfma_f32_32x32x16_bf16 v[48:63], v[128:131], v[132:135], v[48:63]
	v_mfma_f32_32x32x16_bf16 v[16:31], v[128:131], v[154:157], v[16:31]
	v_subrev_u32_e32 v131, 36, v152
	v_mov_b32_e32 v128, v147
	v_cmp_lt_u32_e32 vcc, 15, v131
	s_and_b64 s[0:1], s[38:39], vcc
	v_bfe_u32 v137, v128, 5, 1
	v_and_b32_e32 v142, 31, v128
	v_mfma_f32_32x32x16_bf16 v[32:47], v[138:141], v[132:135], v[32:47]
	v_mfma_f32_32x32x16_bf16 v[0:15], v[138:141], v[154:157], v[0:15]
	s_and_saveexec_b64 s[4:5], s[0:1]
	s_xor_b64 s[4:5], exec, s[4:5]
	s_cbranch_execz .LBB0_393
	v_cmp_ne_u32_e32 vcc, 34, v152
	s_and_saveexec_b64 s[0:1], vcc
	s_xor_b64 s[6:7], exec, s[0:1]
	s_cbranch_execz .LBB0_390
	s_cmp_gt_u32 s27, 23
	s_mov_b64 s[12:13], -1
	s_cbranch_scc0 .LBB0_373
	v_cmp_lt_u32_e32 vcc, 29, v152
	s_and_saveexec_b64 s[12:13], vcc
	s_xor_b64 s[12:13], exec, s[12:13]
	s_cbranch_execz .LBB0_370
	v_cmp_lt_u32_e32 vcc, 33, v152
	s_and_saveexec_b64 s[16:17], vcc
	s_xor_b64 s[16:17], exec, s[16:17]
	s_cbranch_execz .LBB0_367
	s_cmp_gt_u32 s27, 59
	s_mov_b64 s[0:1], -1
	s_cbranch_scc0 .LBB0_363
	s_cmpk_gt_u32 s27, 0x53
	v_lshlrev_b32_e32 v129, 6, v152
	s_mov_b64 s[8:9], -1
	s_mov_b64 s[10:11], -1
	s_cbranch_scc0 .LBB0_361
	s_add_u32 s14, s2, 0x11fd6100
	s_addc_u32 s15, s3, 0
	v_add_u32_e32 v128, 0xffffeb00, v129
	s_mov_b64 s[10:11], 0
